# PEER up phase layers 0-2 column-sliced per XCD group (L2-resident 2MiB table slices), select-loop counting rewrite
# speedup vs baseline: 1.0593x; 1.0593x over previous
; __device__ __forceinline__ void cvt_fp8(const Ctx& C, const float* src, unsigned char* dst, size_t n, float sc, const float* gain  ) {
;     int lane = threadIdx.x & 63; asm volatile("" : "+v"(lane));
;     const size_t nth = (size_t)C.ngw * 64, n16 = n / 16;
;     for (size_t i = (size_t)C.gw * 64 + lane; i < n16; i += 2 * nth) {
;         const size_t i2 = i + nth; const bool has2 = i2 < n16;
;         const f32x4* sp = (const f32x4*)(src + i * 16); const f32x4* sp2 = (const f32x4*)(src + (has2 ? i2 : i) * 16);
; __global__ void __launch_bounds__(512, 2) mk_fwd(Args a) {
;     ...
;             if (ph == 0 || l > 0) { cvt_fp8(C, a.in[16] + (size_t)l * NEXP * DM, EXP8, (size_t)NEXP * DM, EXP_SC_D, a.in[13] + l * DM); cvt_fp8(C, a.in[17] + (size_t)l * NEXP * DM, EXP8 + (size_t)NEXP * DM, (size_t)NEXP * DM, EXP_SC_U, nullptr); }
.LBB0_127:
	s_or_b64 exec, exec, s[12:13]
	v_mov_b32_e32 v2, v177
	s_mov_b64 s[0:1], 0x100000
	v_ashrrev_i32_e32 v3, 31, v2
	v_lshl_add_u64 v[0:1], s[10:11], 0, v[2:3]
	v_cmp_gt_u64_e32 vcc, s[0:1], v[0:1]
	s_and_saveexec_b64 s[0:1], vcc
	s_cbranch_execz .LBB0_132
	v_readlane_b32 s16, v249, 0
	v_readlane_b32 s17, v249, 1
	s_lshl_b64 s[6:7], s[6:7], 2
	v_readlane_b32 s18, v249, 2
	v_readlane_b32 s12, v247, 56
	v_readlane_b32 s16, v247, 53
	v_readlane_b32 s19, v249, 3
	s_add_u32 s6, s18, s6
	v_readlane_b32 s13, v247, 57
	v_readlane_b32 s17, v247, 54
	s_addc_u32 s7, s19, s7
	s_lshl_b64 s[12:13], s[12:13], 26
	s_lshl_b64 s[14:15], s[16:17], 12
	s_add_u32 s2, s12, s14
	s_addc_u32 s13, s13, s15
	s_add_u32 s12, s18, s2
	v_lshlrev_b64 v[4:5], 6, v[2:3]
	s_addc_u32 s13, s19, s13
	v_lshl_add_u64 v[20:21], s[12:13], 0, v[4:5]
	s_lshl_b64 s[12:13], s[16:17], 10
	s_add_u32 s10, s36, s10
	s_addc_u32 s11, s37, s11
	v_lshl_add_u64 v[22:23], v[2:3], 4, s[12:13]
	v_lshl_add_u64 v[2:3], s[10:11], 0, v[2:3]
	v_readlane_b32 s12, v249, 37
	v_lshlrev_b64 v[24:25], 4, v[2:3]
	s_mov_b64 s[10:11], 0
	v_readlane_b32 s13, v249, 38
	v_readlane_b32 s20, v249, 4
	v_readlane_b32 s21, v249, 5
	v_readlane_b32 s22, v249, 6
	v_readlane_b32 s23, v249, 7
	v_readlane_b32 s16, v249, 37
	v_readlane_b32 s17, v249, 38
	v_readlane_b32 s18, v247, 56
	s_branch .LBB0_130

; __device__ __forceinline__ unsigned pack_fp8x4(f32x4 v, float sc) { int r = 0; r = __builtin_amdgcn_cvt_pk_fp8_f32(v.x * sc, v.y * sc, r, false); r = __builtin_amdgcn_cvt_pk_fp8_f32(v.z * sc, v.w * sc, r, true); return (unsigned)r; }
; __device__ __forceinline__ void cvt_fp8(const Ctx& C, const float* src, unsigned char* dst, size_t n, float sc, const float* gain  ) {
;     ...
;     for (size_t i = (size_t)C.gw * 64 + lane; i < n16; i += 2 * nth) {
;         const size_t i2 = i + nth; const bool has2 = i2 < n16;
;         const f32x4* sp = (const f32x4*)(src + i * 16); const f32x4* sp2 = (const f32x4*)(src + (has2 ? i2 : i) * 16);
;         f32x4 a = sp[0], b = sp[1], c = sp[2], d = sp[3], a2 = sp2[0], b2 = sp2[1], c2 = sp2[2], d2 = sp2[3];
;         if (gain) { const f32x4* gp = (const f32x4*)(gain + ((i * 16) & 1023)); a = a * gp[0]; b = b * gp[1]; c = c * gp[2]; d = d * gp[3];
;                     const f32x4* gq = (const f32x4*)(gain + (((has2 ? i2 : i) * 16) & 1023)); a2 = a2 * gq[0]; b2 = b2 * gq[1]; c2 = c2 * gq[2]; d2 = d2 * gq[3]; }
;         v4u o; o.x = pack_fp8x4(a, sc); o.y = pack_fp8x4(b, sc); o.z = pack_fp8x4(c, sc); o.w = pack_fp8x4(d, sc);
;         *(v4u*)(dst + i * 16) = o;
;         if (has2) { v4u o2; o2.x = pack_fp8x4(a2, sc); o2.y = pack_fp8x4(b2, sc); o2.z = pack_fp8x4(c2, sc); o2.w = pack_fp8x4(d2, sc); *(v4u*)(dst + i2 * 16) = o2; }
.LBB0_130:
	v_lshl_add_u64 v[26:27], v[0:1], 0, s[36:37]
	s_mov_b64 s[14:15], 0x100000
	v_cmp_gt_u64_e32 vcc, s[14:15], v[26:27]
	s_nop 1
	v_cndmask_b32_e32 v1, v1, v27, vcc
	v_cndmask_b32_e32 v0, v0, v26, vcc
	v_lshlrev_b64 v[0:1], 6, v[0:1]
	v_lshl_add_u64 v[16:17], s[6:7], 0, v[0:1]
	global_load_dwordx4 v[0:3], v[20:21], off offset:48
	global_load_dwordx4 v[28:31], v[20:21], off offset:32
	global_load_dwordx4 v[32:35], v[20:21], off offset:16
	global_load_dwordx4 v[36:39], v[20:21], off
	global_load_dwordx4 v[4:7], v[16:17], off offset:48
	s_waitcnt lgkmcnt(0)
	global_load_dwordx4 v[8:11], v[16:17], off offset:32
	global_load_dwordx4 v[12:15], v[16:17], off offset:16
	s_nop 0
	global_load_dwordx4 v[16:19], v[16:17], off
	s_waitcnt vmcnt(0)
	v_mul_f32_e32 v0, 0x42800000, v0
	v_mul_f32_e32 v28, 0x42800000, v28
	v_mul_f32_e32 v32, 0x42800000, v32
	v_mul_f32_e32 v40, 0x42800000, v36
	v_mul_f32_e32 v37, 0x42800000, v37
	v_mov_b32_e32 v36, v137
	v_cvt_pk_fp8_f32 v36, v40, v37
	v_mul_f32_e32 v37, 0x42800000, v38
	v_mul_f32_e32 v38, 0x42800000, v39
	v_mul_f32_e32 v33, 0x42800000, v33
	v_cvt_pk_fp8_f32 v36, v37, v38 op_sel:[0,0,1]
	v_mov_b32_e32 v37, v137
	v_mul_f32_e32 v29, 0x42800000, v29
	v_mov_b32_e32 v38, v137
	v_mul_f32_e32 v1, 0x42800000, v1
	v_mov_b32_e32 v39, v137
	v_cvt_pk_fp8_f32 v37, v32, v33
	v_cvt_pk_fp8_f32 v38, v28, v29
	v_cvt_pk_fp8_f32 v39, v0, v1
	v_mul_f32_e32 v32, 0x42800000, v34
	v_mul_f32_e32 v33, 0x42800000, v35
	v_mul_f32_e32 v28, 0x42800000, v30
	v_mul_f32_e32 v29, 0x42800000, v31
	v_mul_f32_e32 v0, 0x42800000, v2
	v_mul_f32_e32 v1, 0x42800000, v3
	v_cvt_pk_fp8_f32 v37, v32, v33 op_sel:[0,0,1]
	v_cvt_pk_fp8_f32 v38, v28, v29 op_sel:[0,0,1]
	v_cvt_pk_fp8_f32 v39, v0, v1 op_sel:[0,0,1]
	v_lshl_add_u64 v[0:1], s[12:13], 0, v[22:23]
	s_cmp_gt_u32 s18, 2
	s_cbranch_scc1 .Lcvt_skip1
	v_subrev_u32_e32 v42, s16, v0
	v_lshrrev_b32_e32 v43, 10, v42
	v_bfe_u32 v44, v42, 7, 3
	v_and_b32_e32 v42, 0x7f, v42
	v_lshl_or_b32 v42, v43, 7, v42
	v_lshl_or_b32 v42, v44, 21, v42
	v_mov_b32_e32 v43, 0
	v_lshl_add_u64 v[0:1], s[16:17], 0, v[42:43]
.Lcvt_skip1:
	global_store_dwordx4 v[0:1], v[36:39], off
	s_and_saveexec_b64 s[14:15], vcc
	s_cbranch_execz .LBB0_129
	v_mul_f32_e32 v1, 0x42800000, v16
	v_mul_f32_e32 v2, 0x42800000, v17
	v_mov_b32_e32 v0, v137
	v_cvt_pk_fp8_f32 v0, v1, v2
	v_mul_f32_e32 v12, 0x42800000, v12
	v_mul_f32_e32 v13, 0x42800000, v13
	v_mov_b32_e32 v1, v137
	v_cvt_pk_fp8_f32 v1, v12, v13
	v_mul_f32_e32 v2, 0x42800000, v18
	v_mul_f32_e32 v3, 0x42800000, v19
	v_cvt_pk_fp8_f32 v0, v2, v3 op_sel:[0,0,1]
	v_mul_f32_e32 v2, 0x42800000, v14
	v_mul_f32_e32 v3, 0x42800000, v15
	v_cvt_pk_fp8_f32 v1, v2, v3 op_sel:[0,0,1]
	v_mul_f32_e32 v3, 0x42800000, v8
	v_mul_f32_e32 v8, 0x42800000, v9
	v_mov_b32_e32 v2, v137
	v_cvt_pk_fp8_f32 v2, v3, v8
	v_mul_f32_e32 v4, 0x42800000, v4
	v_mul_f32_e32 v5, 0x42800000, v5
	v_mov_b32_e32 v3, v137
	v_cvt_pk_fp8_f32 v3, v4, v5
	v_mul_f32_e32 v8, 0x42800000, v10
	v_mul_f32_e32 v9, 0x42800000, v11
	v_mul_f32_e32 v4, 0x42800000, v6
	v_mul_f32_e32 v5, 0x42800000, v7
	v_cvt_pk_fp8_f32 v2, v8, v9 op_sel:[0,0,1]
	v_cvt_pk_fp8_f32 v3, v4, v5 op_sel:[0,0,1]
	v_lshl_add_u64 v[4:5], s[12:13], 0, v[24:25]
	s_cmp_gt_u32 s18, 2
	s_cbranch_scc1 .Lcvt_skip2
	v_subrev_u32_e32 v42, s16, v4
	v_lshrrev_b32_e32 v43, 10, v42
	v_bfe_u32 v44, v42, 7, 3
	v_and_b32_e32 v42, 0x7f, v42
	v_lshl_or_b32 v42, v43, 7, v42
	v_lshl_or_b32 v42, v44, 21, v42
	v_mov_b32_e32 v43, 0
	v_lshl_add_u64 v[4:5], s[16:17], 0, v[42:43]
.Lcvt_skip2:
	global_store_dwordx4 v[4:5], v[0:3], off
	s_branch .LBB0_129

; #define SK_LOAD(KF, P_) do { _Pragma("unroll") for (int t = 0; t < 2; ++t) _Pragma("unroll") for (int ks = 0; ks < 4; ++ks) KF[t][ks] = *(const bf16x8*)(kp0 + (size_t)(16 * (2 * (P_) + t)) * 128 + 32 * ks); } while (0)
; #define SK_MMA(KF, P_) do { _Pragma("unroll") for (int t = 0; t < 2; ++t) { st[2 * (P_) + t] = (f32x4){0.f, 0.f, 0.f, 0.f}; \
;                       _Pragma("unroll") for (int ks = 0; ks < 4; ++ks) st[2 * (P_) + t] = __builtin_amdgcn_mfma_f32_16x16x32_bf16(KF[t][ks], qf[ks], st[2 * (P_) + t], 0, 0, 0); } } while (0)
; __device__ __forceinline__ void peer_phase(const Ctx& C, const bf16* PQ, const bf16* SK  , const unsigned char* ED, const unsigned char* EU, const bf16* HB  , bf16* XBN  , float* RSS, float* xio, const float* gfinal, bool last, float* SELG, int* SELI) {
;     ...
;                   bf16x8 kfA[2][4], kfB[2][4];
;                   const bf16* kp0 = SK + (size_t)(c * 128 + i) * 128 + 8 * g;
;     ...
;                   SK_LOAD(kfA, 0);
;                   SK_LOAD(kfB, 1); asm volatile("" ::: "memory");
;                   SK_MMA(kfA, 0); SK_LOAD(kfA, 2); asm volatile("" ::: "memory");
;                   SK_MMA(kfB, 1); SK_LOAD(kfB, 3); asm volatile("" ::: "memory");
;                   SK_MMA(kfA, 2); SK_MMA(kfB, 3);
;     ...
;                 }
;                 float lo, hi;
;                 { float mn = st[0][0], mx = st[0][0];
; #pragma unroll
;                   for (int kt = 0; kt < 8; ++kt)
; #pragma unroll
;                       for (int j = 0; j < 4; ++j) { mn = fminf(mn, st[kt][j]); mx = fmaxf(mx, st[kt][j]); }
;                   mn = fminf(mn, __shfl_xor(mn, 16)); mn = fminf(mn, __shfl_xor(mn, 32)); mx = fmaxf(mx, __shfl_xor(mx, 16)); mx = fmaxf(mx, __shfl_xor(mx, 32));
.LBB0_157:
	v_lshlrev_b32_e32 v16, 1, v86
	v_lshl_or_b32 v136, s93, 15, v16
	v_lshl_add_u64 v[82:83], v[74:75], 0, v[136:137]
	global_load_dwordx4 v[16:19], v[82:83], off
	global_load_dwordx4 v[20:23], v[82:83], off offset:64
	global_load_dwordx4 v[130:133], v[82:83], off offset:128
	global_load_dwordx4 v[142:145], v[82:83], off offset:192
	v_add_co_u32_e32 v24, vcc, 0x1000, v82
	s_xor_b64 s[70:71], s[0:1], -1
	s_nop 0
	v_addc_co_u32_e32 v25, vcc, 0, v83, vcc
	s_movk_i32 s0, 0x2000
	v_add_co_u32_e32 v36, vcc, s0, v82
	s_movk_i32 s0, 0x3000
	s_nop 0
	v_addc_co_u32_e32 v37, vcc, 0, v83, vcc
	v_add_co_u32_e32 v68, vcc, s0, v82
	global_load_dwordx4 v[146:149], v[24:25], off
	global_load_dwordx4 v[150:153], v[24:25], off offset:64
	global_load_dwordx4 v[154:157], v[24:25], off offset:128
	global_load_dwordx4 v[158:161], v[24:25], off offset:192
	v_addc_co_u32_e32 v69, vcc, 0, v83, vcc
	global_load_dwordx4 v[24:27], v[68:69], off offset:-4096
	global_load_dwordx4 v[28:31], v[36:37], off offset:64
	global_load_dwordx4 v[32:35], v[36:37], off offset:128
	s_nop 0
	global_load_dwordx4 v[36:39], v[36:37], off offset:192
	s_nop 0
	global_load_dwordx4 v[44:47], v[68:69], off
	global_load_dwordx4 v[60:63], v[68:69], off offset:64
	global_load_dwordx4 v[64:67], v[68:69], off offset:128
	s_nop 0
	global_load_dwordx4 v[68:71], v[68:69], off offset:192
	s_movk_i32 s0, 0x4000
	v_add_co_u32_e32 v134, vcc, s0, v82
	s_movk_i32 s0, 0x5000
	s_nop 0
	v_addc_co_u32_e32 v135, vcc, 0, v83, vcc
	v_add_co_u32_e32 v166, vcc, s0, v82
	s_movk_i32 s0, 0x6000
	s_nop 0
	v_addc_co_u32_e32 v167, vcc, 0, v83, vcc
	s_mov_b32 s2, 0
	s_waitcnt vmcnt(15)
	v_mfma_f32_16x16x32_bf16 v[16:19], v[16:19], v[40:43], 0
	s_waitcnt vmcnt(14)
	v_mfma_f32_16x16x32_bf16 v[16:19], v[20:23], v[48:51], v[16:19]
	s_waitcnt vmcnt(13)
	v_mfma_f32_16x16x32_bf16 v[16:19], v[130:133], v[52:55], v[16:19]
	s_waitcnt vmcnt(7)
	v_mfma_f32_16x16x32_bf16 v[24:27], v[24:27], v[40:43], 0
	v_mfma_f32_16x16x32_bf16 v[20:23], v[142:145], v[56:59], v[16:19]
	v_mfma_f32_16x16x32_bf16 v[16:19], v[146:149], v[40:43], 0
	s_waitcnt vmcnt(6)
	v_mfma_f32_16x16x32_bf16 v[24:27], v[28:31], v[48:51], v[24:27]
	v_mfma_f32_16x16x32_bf16 v[16:19], v[150:153], v[48:51], v[16:19]
	s_waitcnt vmcnt(5)
	v_mfma_f32_16x16x32_bf16 v[24:27], v[32:35], v[52:55], v[24:27]
	v_add_co_u32_e32 v32, vcc, s0, v82
	s_movk_i32 s0, 0x7000
	v_mfma_f32_16x16x32_bf16 v[16:19], v[154:157], v[52:55], v[16:19]
	v_addc_co_u32_e32 v33, vcc, 0, v83, vcc
	v_add_co_u32_e32 v34, vcc, s0, v82
	s_waitcnt vmcnt(4)
	v_mfma_f32_16x16x32_bf16 v[28:31], v[36:39], v[56:59], v[24:27]
	v_addc_co_u32_e32 v35, vcc, 0, v83, vcc
	s_mov_b64 s[0:1], 0
	s_waitcnt vmcnt(3)
	v_mfma_f32_16x16x32_bf16 v[24:27], v[44:47], v[40:43], 0
	v_mfma_f32_16x16x32_bf16 v[16:19], v[158:161], v[56:59], v[16:19]
	global_load_dwordx4 v[130:133], v[166:167], off offset:-4096
	global_load_dwordx4 v[142:145], v[134:135], off offset:64
	global_load_dwordx4 v[146:149], v[134:135], off offset:128
	global_load_dwordx4 v[150:153], v[134:135], off offset:192
	global_load_dwordx4 v[154:157], v[166:167], off
	global_load_dwordx4 v[158:161], v[166:167], off offset:64
	global_load_dwordx4 v[162:165], v[166:167], off offset:128
	s_nop 0
	global_load_dwordx4 v[166:169], v[166:167], off offset:192
	s_waitcnt vmcnt(10)
	v_mfma_f32_16x16x32_bf16 v[24:27], v[60:63], v[48:51], v[24:27]
	s_waitcnt vmcnt(9)
	v_mfma_f32_16x16x32_bf16 v[24:27], v[64:67], v[52:55], v[24:27]
	s_waitcnt vmcnt(8)
	v_mfma_f32_16x16x32_bf16 v[24:27], v[68:71], v[56:59], v[24:27]
	global_load_dwordx4 v[44:47], v[34:35], off offset:-4096
	global_load_dwordx4 v[60:63], v[32:33], off offset:64
	global_load_dwordx4 v[64:67], v[32:33], off offset:128
	global_load_dwordx4 v[68:71], v[32:33], off offset:192
	global_load_dwordx4 v[170:173], v[34:35], off
	global_load_dwordx4 v[190:193], v[34:35], off offset:64
	global_load_dwordx4 v[194:197], v[34:35], off offset:128
	global_load_dwordx4 v[198:201], v[34:35], off offset:192
	s_waitcnt vmcnt(15)
	v_mfma_f32_16x16x32_bf16 v[32:35], v[130:133], v[40:43], 0
	s_waitcnt vmcnt(14)
	v_mfma_f32_16x16x32_bf16 v[32:35], v[142:145], v[48:51], v[32:35]
	s_waitcnt vmcnt(13)
	v_mfma_f32_16x16x32_bf16 v[32:35], v[146:149], v[52:55], v[32:35]
	s_waitcnt vmcnt(12)
	v_mfma_f32_16x16x32_bf16 v[36:39], v[150:153], v[56:59], v[32:35]
	s_waitcnt vmcnt(11)
	v_mfma_f32_16x16x32_bf16 v[32:35], v[154:157], v[40:43], 0
	s_waitcnt vmcnt(7)
	v_mfma_f32_16x16x32_bf16 v[44:47], v[44:47], v[40:43], 0
	s_waitcnt vmcnt(3)
	v_mfma_f32_16x16x32_bf16 v[40:43], v[170:173], v[40:43], 0
	v_mfma_f32_16x16x32_bf16 v[32:35], v[158:161], v[48:51], v[32:35]
	v_mfma_f32_16x16x32_bf16 v[44:47], v[60:63], v[48:51], v[44:47]
	s_waitcnt vmcnt(2)
	v_mfma_f32_16x16x32_bf16 v[40:43], v[190:193], v[48:51], v[40:43]
	v_max_f32_e32 v48, v21, v21
	v_max_f32_e32 v49, v20, v20
	v_min_f32_e32 v50, v49, v48
	v_max_f32_e32 v48, v49, v48
	v_max3_f32 v48, v48, v22, v23
	v_mfma_f32_16x16x32_bf16 v[32:35], v[162:165], v[52:55], v[32:35]
	v_max3_f32 v48, v48, v16, v17
	v_max3_f32 v48, v48, v18, v19
	v_min3_f32 v49, v50, v22, v23
	v_mfma_f32_16x16x32_bf16 v[44:47], v[64:67], v[52:55], v[44:47]
	v_max3_f32 v48, v48, v28, v29
	v_min3_f32 v49, v49, v16, v17
	v_max3_f32 v48, v48, v30, v31
	v_mfma_f32_16x16x32_bf16 v[32:35], v[166:169], v[56:59], v[32:35]
	v_min3_f32 v49, v49, v18, v19
	v_max3_f32 v48, v48, v24, v25
	v_min3_f32 v49, v49, v28, v29
	s_waitcnt vmcnt(1)
; __device__ __forceinline__ void peer_phase(const Ctx& C, const bf16* PQ, const bf16* SK  , const unsigned char* ED, const unsigned char* EU, const bf16* HB  , bf16* XBN  , float* RSS, float* xio, const float* gfinal, bool last, float* SELG, int* SELI) {
;     ...
;                   mn = fminf(mn, __shfl_xor(mn, 16)); mn = fminf(mn, __shfl_xor(mn, 32)); mx = fmaxf(mx, __shfl_xor(mx, 16)); mx = fmaxf(mx, __shfl_xor(mx, 32));
;                   lo = mn; hi = mx; }
;                 bool done = false;
;                 for (int it = 0; it < 64; ++it) {
;                     const float mid = 0.5f * (lo + hi); int cnt = 0;
; #pragma unroll
;                     for (int kt = 0; kt < 8; ++kt)
; #pragma unroll
;                         for (int j = 0; j < 4; ++j) cnt += (st[kt][j] >= mid) ? 1 : 0;
;                     cnt += __shfl_xor(cnt, 16); cnt += __shfl_xor(cnt, 32);
;                     if (!done) { if (!(mid > lo && mid < hi)) done = true; else if (cnt >= 16) { lo = mid; done = (cnt == 16); } else hi = mid; }
;                     if (__all(done ? 1 : 0)) break;
;                 }
	v_mfma_f32_16x16x32_bf16 v[40:43], v[194:197], v[52:55], v[40:43]
	v_max3_f32 v48, v48, v26, v27
	v_min3_f32 v49, v49, v30, v31
	v_max3_f32 v48, v48, v36, v37
	v_mfma_f32_16x16x32_bf16 v[44:47], v[68:71], v[56:59], v[44:47]
	v_min3_f32 v49, v49, v24, v25
	v_max3_f32 v48, v48, v38, v39
	v_min3_f32 v49, v49, v26, v27
	s_waitcnt vmcnt(0)
	v_mfma_f32_16x16x32_bf16 v[40:43], v[198:201], v[56:59], v[40:43]
	v_max3_f32 v48, v48, v32, v33
	v_min3_f32 v49, v49, v36, v37
	v_max3_f32 v48, v48, v34, v35
	v_min3_f32 v49, v49, v38, v39
	v_max3_f32 v48, v48, v44, v45
	v_min3_f32 v49, v49, v32, v33
	v_max3_f32 v48, v48, v46, v47
	v_min3_f32 v49, v49, v34, v35
	v_max3_f32 v48, v48, v40, v41
	v_and_b32_e32 v50, 64, v181
	v_min3_f32 v49, v49, v44, v45
	v_max3_f32 v52, v48, v42, v43
	v_xor_b32_e32 v48, 16, v181
	v_add_u32_e32 v51, 64, v50
	v_min3_f32 v49, v49, v46, v47
	v_cmp_lt_i32_e32 vcc, v48, v51
	v_min3_f32 v49, v49, v40, v41
	v_min3_f32 v49, v49, v42, v43
	v_cndmask_b32_e32 v48, v181, v48, vcc
	v_lshlrev_b32_e32 v48, 2, v48
	ds_bpermute_b32 v53, v48, v49
	s_waitcnt lgkmcnt(0)
	v_max_f32_e32 v53, v53, v53
	v_min_f32_e32 v53, v49, v53
	v_xor_b32_e32 v49, 32, v181
	v_cmp_lt_i32_e32 vcc, v49, v51
	s_nop 1
	v_cndmask_b32_e32 v49, v181, v49, vcc
	v_lshlrev_b32_e32 v49, 2, v49
	ds_bpermute_b32 v51, v49, v53
	s_waitcnt lgkmcnt(0)
	v_max_f32_e32 v51, v51, v51
	v_min_f32_e32 v51, v53, v51
	ds_bpermute_b32 v53, v48, v52
	s_waitcnt lgkmcnt(0)
	v_max_f32_e32 v53, v53, v53
	v_max_f32_e32 v52, v52, v53
	ds_bpermute_b32 v53, v49, v52
	s_waitcnt lgkmcnt(0)
	v_max_f32_e32 v53, v53, v53
	v_max_f32_e32 v52, v52, v53
	s_mov_b64 s[4:5], 0
	s_mov_b32 s2, 0
	s_waitcnt lgkmcnt(0)
.LselA_loop:
	v_add_f32_e32 v53, v52, v51
	v_mul_f32_e32 v53, 0.5, v53
	v_cmp_ge_f32_e64 s[0:1], v21, v53
	v_cmp_ge_f32_e64 s[6:7], v20, v53
	v_cmp_ge_f32_e64 s[8:9], v22, v53
	v_addc_co_u32_e64 v54, vcc, 0, 0, s[0:1]
	v_cmp_ge_f32_e64 s[0:1], v23, v53
	v_addc_co_u32_e64 v55, vcc, 0, 0, s[6:7]
	v_cmp_ge_f32_e64 s[6:7], v16, v53
	v_addc_co_u32_e64 v54, vcc, 0, v54, s[8:9]
	v_cmp_ge_f32_e64 s[8:9], v17, v53
	v_addc_co_u32_e64 v55, vcc, 0, v55, s[0:1]
	v_cmp_ge_f32_e64 s[0:1], v18, v53
	v_addc_co_u32_e64 v54, vcc, 0, v54, s[6:7]
	v_cmp_ge_f32_e64 s[6:7], v19, v53
	v_addc_co_u32_e64 v55, vcc, 0, v55, s[8:9]
	v_cmp_ge_f32_e64 s[8:9], v28, v53
	v_addc_co_u32_e64 v54, vcc, 0, v54, s[0:1]
	v_cmp_ge_f32_e64 s[0:1], v29, v53
	v_addc_co_u32_e64 v55, vcc, 0, v55, s[6:7]
	v_cmp_ge_f32_e64 s[6:7], v30, v53
	v_addc_co_u32_e64 v54, vcc, 0, v54, s[8:9]
	v_cmp_ge_f32_e64 s[8:9], v31, v53
	v_addc_co_u32_e64 v55, vcc, 0, v55, s[0:1]
	v_cmp_ge_f32_e64 s[0:1], v24, v53
	v_addc_co_u32_e64 v54, vcc, 0, v54, s[6:7]
	v_cmp_ge_f32_e64 s[6:7], v25, v53
	v_addc_co_u32_e64 v55, vcc, 0, v55, s[8:9]
	v_cmp_ge_f32_e64 s[8:9], v26, v53
	v_addc_co_u32_e64 v54, vcc, 0, v54, s[0:1]
	v_cmp_ge_f32_e64 s[0:1], v27, v53
	v_addc_co_u32_e64 v55, vcc, 0, v55, s[6:7]
	v_cmp_ge_f32_e64 s[6:7], v36, v53
	v_addc_co_u32_e64 v54, vcc, 0, v54, s[8:9]
	v_cmp_ge_f32_e64 s[8:9], v37, v53
	v_addc_co_u32_e64 v55, vcc, 0, v55, s[0:1]
	v_cmp_ge_f32_e64 s[0:1], v38, v53
	v_addc_co_u32_e64 v54, vcc, 0, v54, s[6:7]
	v_cmp_ge_f32_e64 s[6:7], v39, v53
	v_addc_co_u32_e64 v55, vcc, 0, v55, s[8:9]
	v_cmp_ge_f32_e64 s[8:9], v32, v53
	v_addc_co_u32_e64 v54, vcc, 0, v54, s[0:1]
	v_cmp_ge_f32_e64 s[0:1], v33, v53
	v_addc_co_u32_e64 v55, vcc, 0, v55, s[6:7]
	v_cmp_ge_f32_e64 s[6:7], v34, v53
	v_addc_co_u32_e64 v54, vcc, 0, v54, s[8:9]
	v_cmp_ge_f32_e64 s[8:9], v35, v53
	v_addc_co_u32_e64 v55, vcc, 0, v55, s[0:1]
	v_cmp_ge_f32_e64 s[0:1], v44, v53
	v_addc_co_u32_e64 v54, vcc, 0, v54, s[6:7]
	v_cmp_ge_f32_e64 s[6:7], v45, v53
	v_addc_co_u32_e64 v55, vcc, 0, v55, s[8:9]
	v_cmp_ge_f32_e64 s[8:9], v46, v53
	v_addc_co_u32_e64 v54, vcc, 0, v54, s[0:1]
	v_cmp_ge_f32_e64 s[0:1], v47, v53
	v_addc_co_u32_e64 v55, vcc, 0, v55, s[6:7]
	v_cmp_ge_f32_e64 s[6:7], v40, v53
	v_addc_co_u32_e64 v54, vcc, 0, v54, s[8:9]
	v_cmp_ge_f32_e64 s[8:9], v41, v53
	v_addc_co_u32_e64 v55, vcc, 0, v55, s[0:1]
	v_cmp_ge_f32_e64 s[0:1], v42, v53
	v_addc_co_u32_e64 v54, vcc, 0, v54, s[6:7]
	v_cmp_ge_f32_e64 s[6:7], v43, v53
	v_addc_co_u32_e64 v55, vcc, 0, v55, s[8:9]
	v_addc_co_u32_e64 v54, vcc, 0, v54, s[0:1]
	v_addc_co_u32_e64 v55, vcc, 0, v55, s[6:7]
	v_add_u32_e32 v54, v54, v55
	v_cmp_gt_f32_e64 s[0:1], v53, v51
	v_mov_b32_e32 v55, v54
	v_cmp_lt_f32_e64 s[6:7], v53, v52
	s_nop 1
	v_permlane16_swap_b32_e32 v54, v55
	s_and_b64 s[0:1], s[0:1], s[6:7]
	v_add_u32_e32 v54, v54, v55
	s_andn2_b64 s[6:7], s[0:1], s[4:5]
	v_mov_b32_e32 v55, v54
	s_orn2_b64 s[4:5], s[4:5], s[0:1]
	s_nop 1
	v_permlane32_swap_b32_e32 v54, v55
	s_add_i32 s2, s2, 1
	v_add_u32_e32 v54, v54, v55
	v_cmp_lt_i32_e64 s[8:9], 15, v54
	v_cmp_eq_u32_e64 s[10:11], 16, v54
	s_and_b64 s[0:1], s[6:7], s[8:9]
	s_andn2_b64 s[6:7], s[6:7], s[8:9]
	s_and_b64 s[10:11], s[0:1], s[10:11]
	v_cndmask_b32_e64 v51, v51, v53, s[0:1]
	v_cndmask_b32_e64 v52, v52, v53, s[6:7]
	s_or_b64 s[4:5], s[4:5], s[10:11]
	s_cmp_eq_u64 s[4:5], exec
	s_cbranch_scc1 .LBB0_166
	s_cmp_lt_u32 s2, 64
	s_cbranch_scc1 .LselA_loop

; __device__ __forceinline__ void peer_phase(const Ctx& C, const bf16* PQ, const bf16* SK  , const unsigned char* ED, const unsigned char* EU, const bf16* HB  , bf16* XBN  , float* RSS, float* xio, const float* gfinal, bool last, float* SELG, int* SELI) {
;     ...
;             float s0[4], s1[16]; int i0[4];
; #pragma unroll
;             for (int a = 0; a < 4; ++a) { s0[a] = ls[(0 * 16 + i) * 16 + 4 * g + a]; i0[a] = li[(0 * 16 + i) * 16 + 4 * g + a]; }
; #pragma unroll
;             for (int bb = 0; bb < 16; ++bb) s1[bb] = ls[(1 * 16 + i) * 16 + bb];
;             float cs[64];
; #pragma unroll
;             for (int a = 0; a < 4; ++a)
; #pragma unroll
;                 for (int bb = 0; bb < 16; ++bb) cs[a * 16 + bb] = s0[a] + s1[bb];
;             float lo, hi;
;             { float mn = cs[0], mx = cs[0];
; #pragma unroll
;               for (int r = 1; r < 64; ++r) { mn = fminf(mn, cs[r]); mx = fmaxf(mx, cs[r]); }
;               mn = fminf(mn, __shfl_xor(mn, 16)); mn = fminf(mn, __shfl_xor(mn, 32)); mx = fmaxf(mx, __shfl_xor(mx, 16)); mx = fmaxf(mx, __shfl_xor(mx, 32));
;               lo = mn; hi = mx; }
;             bool done = false;
.LBB0_178:
	ds_read_b128 v[16:19], v93 offset:1072
	ds_read_b128 v[22:25], v93 offset:1024
	ds_read_b128 v[156:159], v125
	ds_read_b128 v[40:43], v93 offset:1056
	ds_read_b128 v[44:47], v93 offset:1040
	s_waitcnt lgkmcnt(4)
	v_mov_b32_e32 v26, v19
	s_waitcnt lgkmcnt(3)
	v_mov_b32_e32 v27, v22
	s_waitcnt lgkmcnt(2)
	v_add_f32_e32 v154, v156, v23
	v_add_f32_e32 v20, v156, v22
	v_add_f32_e32 v153, v156, v24
	v_add_f32_e32 v152, v156, v25
	s_waitcnt lgkmcnt(0)
	v_add_f32_e32 v150, v156, v44
	v_add_f32_e32 v33, v156, v43
	v_add_f32_e32 v32, v156, v16
	v_add_f32_e32 v142, v157, v44
	v_add_f32_e32 v132, v157, v43
	v_add_f32_e32 v131, v157, v16
	v_add_f32_e32 v67, v158, v44
	v_add_f32_e32 v60, v158, v43
	v_add_f32_e32 v59, v158, v16
	v_add_f32_e32 v53, v159, v44
	v_add_f32_e32 v44, v159, v43
	v_add_f32_e32 v43, v159, v16
	v_min_f32_e32 v16, v20, v154
	v_add_f32_e32 v31, v156, v45
	v_add_f32_e32 v34, v156, v42
	v_add_f32_e32 v148, v156, v17
	v_add_f32_e32 v141, v157, v45
	v_add_f32_e32 v133, v157, v42
	v_add_f32_e32 v130, v157, v17
	v_add_f32_e32 v66, v158, v45
	v_add_f32_e32 v61, v158, v42
	v_add_f32_e32 v58, v158, v17
	v_add_f32_e32 v52, v159, v45
	v_add_f32_e32 v45, v159, v42
	v_add_f32_e32 v42, v159, v17
	v_max_f32_e32 v17, v20, v154
	v_min3_f32 v16, v16, v153, v152
	v_add_f32_e32 v30, v156, v46
	v_add_f32_e32 v29, v156, v47
	v_max3_f32 v17, v17, v153, v152
	v_min3_f32 v16, v16, v150, v31
	v_add_f32_e32 v28, v156, v40
	v_add_f32_e32 v35, v156, v41
	v_max3_f32 v17, v17, v150, v31
	v_min3_f32 v16, v16, v30, v29
	v_max3_f32 v17, v17, v30, v29
	v_min3_f32 v16, v16, v28, v35
	v_max3_f32 v17, v17, v28, v35
	v_min3_f32 v16, v16, v34, v33
	v_add_f32_e32 v147, v156, v18
	v_pk_add_f32 v[38:39], v[156:157], v[26:27]
	v_max3_f32 v17, v17, v34, v33
	v_min3_f32 v16, v16, v32, v148
	v_add_f32_e32 v146, v157, v23
	v_max3_f32 v17, v17, v32, v148
	v_min3_f32 v16, v16, v147, v38
	v_add_f32_e32 v145, v157, v24
	v_add_f32_e32 v143, v157, v25
	v_max3_f32 v17, v17, v147, v38
	v_min3_f32 v16, v16, v39, v146
	v_max3_f32 v17, v17, v39, v146
	v_min3_f32 v16, v16, v145, v143
	v_add_f32_e32 v139, v157, v46
	v_add_f32_e32 v136, v157, v47
	v_max3_f32 v17, v17, v145, v143
	v_min3_f32 v16, v16, v142, v141
	v_add_f32_e32 v135, v157, v40
	v_add_f32_e32 v134, v157, v41
	v_max3_f32 v17, v17, v142, v141
	v_min3_f32 v16, v16, v139, v136
	v_max3_f32 v17, v17, v139, v136
	v_min3_f32 v16, v16, v135, v134
	v_max3_f32 v17, v17, v135, v134
	v_min3_f32 v16, v16, v133, v132
	v_add_f32_e32 v83, v157, v18
	v_add_f32_e32 v82, v157, v19
	v_max3_f32 v17, v17, v133, v132
	v_min3_f32 v16, v16, v131, v130
	v_add_f32_e32 v71, v158, v22
	v_add_f32_e32 v70, v158, v23
	v_max3_f32 v17, v17, v131, v130
	v_min3_f32 v16, v16, v83, v82
	v_add_f32_e32 v69, v158, v24
	v_add_f32_e32 v68, v158, v25
	v_max3_f32 v17, v17, v83, v82
	v_min3_f32 v16, v16, v71, v70
	v_max3_f32 v17, v17, v71, v70
	v_min3_f32 v16, v16, v69, v68
	v_add_f32_e32 v65, v158, v46
	v_add_f32_e32 v64, v158, v47
	v_max3_f32 v17, v17, v69, v68
	v_min3_f32 v16, v16, v67, v66
	v_add_f32_e32 v63, v158, v40
	v_add_f32_e32 v62, v158, v41
	v_max3_f32 v17, v17, v67, v66
	v_min3_f32 v16, v16, v65, v64
	v_max3_f32 v17, v17, v65, v64
	v_min3_f32 v16, v16, v63, v62
	v_max3_f32 v17, v17, v63, v62
	v_min3_f32 v16, v16, v61, v60
	v_add_f32_e32 v57, v158, v18
	v_pk_add_f32 v[36:37], v[158:159], v[26:27]
	v_max3_f32 v17, v17, v61, v60
	v_min3_f32 v16, v16, v59, v58
	v_add_f32_e32 v56, v159, v23
	v_max3_f32 v17, v17, v59, v58
	v_min3_f32 v16, v16, v57, v36
	v_add_f32_e32 v55, v159, v24
	v_add_f32_e32 v54, v159, v25
	v_max3_f32 v17, v17, v57, v36
	v_min3_f32 v16, v16, v37, v56
	v_max3_f32 v17, v17, v37, v56
	v_min3_f32 v16, v16, v55, v54
	v_add_f32_e32 v51, v159, v46
	v_add_f32_e32 v50, v159, v47
	v_max3_f32 v17, v17, v55, v54
	v_min3_f32 v16, v16, v53, v52
	v_add_f32_e32 v47, v159, v40
	v_add_f32_e32 v46, v159, v41
	v_max3_f32 v17, v17, v53, v52
	v_min3_f32 v16, v16, v51, v50
	v_max3_f32 v17, v17, v51, v50
	v_min3_f32 v16, v16, v47, v46
	v_max3_f32 v17, v17, v47, v46
	v_min3_f32 v16, v16, v45, v44
	v_add_f32_e32 v41, v159, v18
	v_add_f32_e32 v40, v159, v19
	v_max3_f32 v17, v17, v45, v44
	v_min3_f32 v16, v16, v43, v42
	v_min3_f32 v16, v16, v41, v40
	v_max3_f32 v17, v17, v43, v42
	ds_bpermute_b32 v18, v48, v16
	v_max3_f32 v17, v17, v41, v40
	ds_bpermute_b32 v19, v48, v17
	s_mov_b32 s2, 0
	s_waitcnt lgkmcnt(1)
	v_max_f32_e32 v18, v18, v18
	v_min_f32_e32 v21, v16, v18
	s_waitcnt lgkmcnt(0)
	v_max_f32_e32 v16, v19, v19
	ds_bpermute_b32 v23, v49, v21
	v_max_f32_e32 v22, v17, v16
	ds_bpermute_b32 v24, v49, v22
	ds_read_b128 v[16:19], v125 offset:2304
	s_waitcnt lgkmcnt(2)
	v_max_f32_e32 v23, v23, v23
	v_min_f32_e32 v21, v21, v23
	s_waitcnt lgkmcnt(1)
	v_max_f32_e32 v23, v24, v24
	v_max_f32_e32 v22, v22, v23
	s_mov_b64 s[4:5], 0
	s_mov_b32 s2, 0
	s_waitcnt lgkmcnt(0)
; __device__ __forceinline__ void peer_phase(const Ctx& C, const bf16* PQ, const bf16* SK  , const unsigned char* ED, const unsigned char* EU, const bf16* HB  , bf16* XBN  , float* RSS, float* xio, const float* gfinal, bool last, float* SELG, int* SELI) {
;     ...
;             for (int it = 0; it < 64; ++it) {
;                 const float mid = 0.5f * (lo + hi); int cnt = 0;
; #pragma unroll
;                 for (int r = 0; r < 64; ++r) cnt += (cs[r] >= mid) ? 1 : 0;
;                 cnt += __shfl_xor(cnt, 16); cnt += __shfl_xor(cnt, 32);
;                 if (!done) { if (!(mid > lo && mid < hi)) done = true; else if (cnt >= 16) { lo = mid; done = (cnt == 16); } else hi = mid; }
;                 if (__all(done ? 1 : 0)) break;
;             }
.LselB_loop:
	v_add_f32_e32 v23, v22, v21
	v_mul_f32_e32 v23, 0.5, v23
	v_cmp_ge_f32_e64 s[0:1], v154, v23
	v_cmp_ge_f32_e64 s[6:7], v20, v23
	v_cmp_ge_f32_e64 s[8:9], v153, v23
	v_addc_co_u32_e64 v24, vcc, 0, 0, s[0:1]
	v_cmp_ge_f32_e64 s[0:1], v152, v23
	v_addc_co_u32_e64 v25, vcc, 0, 0, s[6:7]
	v_cmp_ge_f32_e64 s[6:7], v150, v23
	v_addc_co_u32_e64 v24, vcc, 0, v24, s[8:9]
	v_cmp_ge_f32_e64 s[8:9], v31, v23
	v_addc_co_u32_e64 v25, vcc, 0, v25, s[0:1]
	v_cmp_ge_f32_e64 s[0:1], v30, v23
	v_addc_co_u32_e64 v24, vcc, 0, v24, s[6:7]
	v_cmp_ge_f32_e64 s[6:7], v29, v23
	v_addc_co_u32_e64 v25, vcc, 0, v25, s[8:9]
	v_cmp_ge_f32_e64 s[8:9], v28, v23
	v_addc_co_u32_e64 v24, vcc, 0, v24, s[0:1]
	v_cmp_ge_f32_e64 s[0:1], v35, v23
	v_addc_co_u32_e64 v25, vcc, 0, v25, s[6:7]
	v_cmp_ge_f32_e64 s[6:7], v34, v23
	v_addc_co_u32_e64 v24, vcc, 0, v24, s[8:9]
	v_cmp_ge_f32_e64 s[8:9], v33, v23
	v_addc_co_u32_e64 v25, vcc, 0, v25, s[0:1]
	v_cmp_ge_f32_e64 s[0:1], v32, v23
	v_addc_co_u32_e64 v24, vcc, 0, v24, s[6:7]
	v_cmp_ge_f32_e64 s[6:7], v148, v23
	v_addc_co_u32_e64 v25, vcc, 0, v25, s[8:9]
	v_cmp_ge_f32_e64 s[8:9], v147, v23
	v_addc_co_u32_e64 v24, vcc, 0, v24, s[0:1]
	v_cmp_ge_f32_e64 s[0:1], v38, v23
	v_addc_co_u32_e64 v25, vcc, 0, v25, s[6:7]
	v_cmp_ge_f32_e64 s[6:7], v39, v23
	v_addc_co_u32_e64 v24, vcc, 0, v24, s[8:9]
	v_cmp_ge_f32_e64 s[8:9], v146, v23
	v_addc_co_u32_e64 v25, vcc, 0, v25, s[0:1]
	v_cmp_ge_f32_e64 s[0:1], v145, v23
	v_addc_co_u32_e64 v24, vcc, 0, v24, s[6:7]
	v_cmp_ge_f32_e64 s[6:7], v143, v23
	v_addc_co_u32_e64 v25, vcc, 0, v25, s[8:9]
	v_cmp_ge_f32_e64 s[8:9], v142, v23
	v_addc_co_u32_e64 v24, vcc, 0, v24, s[0:1]
	v_cmp_ge_f32_e64 s[0:1], v141, v23
	v_addc_co_u32_e64 v25, vcc, 0, v25, s[6:7]
	v_cmp_ge_f32_e64 s[6:7], v139, v23
	v_addc_co_u32_e64 v24, vcc, 0, v24, s[8:9]
	v_cmp_ge_f32_e64 s[8:9], v136, v23
	v_addc_co_u32_e64 v25, vcc, 0, v25, s[0:1]
	v_cmp_ge_f32_e64 s[0:1], v135, v23
	v_addc_co_u32_e64 v24, vcc, 0, v24, s[6:7]
	v_cmp_ge_f32_e64 s[6:7], v134, v23
	v_addc_co_u32_e64 v25, vcc, 0, v25, s[8:9]
	v_cmp_ge_f32_e64 s[8:9], v133, v23
	v_addc_co_u32_e64 v24, vcc, 0, v24, s[0:1]
	v_cmp_ge_f32_e64 s[0:1], v132, v23
	v_addc_co_u32_e64 v25, vcc, 0, v25, s[6:7]
	v_cmp_ge_f32_e64 s[6:7], v131, v23
	v_addc_co_u32_e64 v24, vcc, 0, v24, s[8:9]
	v_cmp_ge_f32_e64 s[8:9], v130, v23
	v_addc_co_u32_e64 v25, vcc, 0, v25, s[0:1]
	v_cmp_ge_f32_e64 s[0:1], v83, v23
	v_addc_co_u32_e64 v24, vcc, 0, v24, s[6:7]
	v_cmp_ge_f32_e64 s[6:7], v82, v23
	v_addc_co_u32_e64 v25, vcc, 0, v25, s[8:9]
	v_cmp_ge_f32_e64 s[8:9], v71, v23
	v_addc_co_u32_e64 v24, vcc, 0, v24, s[0:1]
	v_cmp_ge_f32_e64 s[0:1], v70, v23
	v_addc_co_u32_e64 v25, vcc, 0, v25, s[6:7]
	v_cmp_ge_f32_e64 s[6:7], v69, v23
	v_addc_co_u32_e64 v24, vcc, 0, v24, s[8:9]
	v_cmp_ge_f32_e64 s[8:9], v68, v23
	v_addc_co_u32_e64 v25, vcc, 0, v25, s[0:1]
	v_cmp_ge_f32_e64 s[0:1], v67, v23
	v_addc_co_u32_e64 v24, vcc, 0, v24, s[6:7]
	v_cmp_ge_f32_e64 s[6:7], v66, v23
	v_addc_co_u32_e64 v25, vcc, 0, v25, s[8:9]
	v_cmp_ge_f32_e64 s[8:9], v65, v23
	v_addc_co_u32_e64 v24, vcc, 0, v24, s[0:1]
	v_cmp_ge_f32_e64 s[0:1], v64, v23
	v_addc_co_u32_e64 v25, vcc, 0, v25, s[6:7]
	v_cmp_ge_f32_e64 s[6:7], v63, v23
	v_addc_co_u32_e64 v24, vcc, 0, v24, s[8:9]
	v_cmp_ge_f32_e64 s[8:9], v62, v23
	v_addc_co_u32_e64 v25, vcc, 0, v25, s[0:1]
	v_cmp_ge_f32_e64 s[0:1], v61, v23
	v_addc_co_u32_e64 v24, vcc, 0, v24, s[6:7]
	v_cmp_ge_f32_e64 s[6:7], v60, v23
	v_addc_co_u32_e64 v25, vcc, 0, v25, s[8:9]
	v_cmp_ge_f32_e64 s[8:9], v59, v23
	v_addc_co_u32_e64 v24, vcc, 0, v24, s[0:1]
	v_cmp_ge_f32_e64 s[0:1], v58, v23
	v_addc_co_u32_e64 v25, vcc, 0, v25, s[6:7]
	v_cmp_ge_f32_e64 s[6:7], v57, v23
	v_addc_co_u32_e64 v24, vcc, 0, v24, s[8:9]
	v_cmp_ge_f32_e64 s[8:9], v36, v23
	v_addc_co_u32_e64 v25, vcc, 0, v25, s[0:1]
	v_cmp_ge_f32_e64 s[0:1], v37, v23
	v_addc_co_u32_e64 v24, vcc, 0, v24, s[6:7]
	v_cmp_ge_f32_e64 s[6:7], v56, v23
	v_addc_co_u32_e64 v25, vcc, 0, v25, s[8:9]
	v_cmp_ge_f32_e64 s[8:9], v55, v23
	v_addc_co_u32_e64 v24, vcc, 0, v24, s[0:1]
	v_cmp_ge_f32_e64 s[0:1], v54, v23
	v_addc_co_u32_e64 v25, vcc, 0, v25, s[6:7]
	v_cmp_ge_f32_e64 s[6:7], v53, v23
	v_addc_co_u32_e64 v24, vcc, 0, v24, s[8:9]
	v_cmp_ge_f32_e64 s[8:9], v52, v23
	v_addc_co_u32_e64 v25, vcc, 0, v25, s[0:1]
	v_cmp_ge_f32_e64 s[0:1], v51, v23
	v_addc_co_u32_e64 v24, vcc, 0, v24, s[6:7]
	v_cmp_ge_f32_e64 s[6:7], v50, v23
	v_addc_co_u32_e64 v25, vcc, 0, v25, s[8:9]
	v_cmp_ge_f32_e64 s[8:9], v47, v23
	v_addc_co_u32_e64 v24, vcc, 0, v24, s[0:1]
	v_cmp_ge_f32_e64 s[0:1], v46, v23
	v_addc_co_u32_e64 v25, vcc, 0, v25, s[6:7]
	v_cmp_ge_f32_e64 s[6:7], v45, v23
	v_addc_co_u32_e64 v24, vcc, 0, v24, s[8:9]
	v_cmp_ge_f32_e64 s[8:9], v44, v23
	v_addc_co_u32_e64 v25, vcc, 0, v25, s[0:1]
	v_cmp_ge_f32_e64 s[0:1], v43, v23
	v_addc_co_u32_e64 v24, vcc, 0, v24, s[6:7]
	v_cmp_ge_f32_e64 s[6:7], v42, v23
	v_addc_co_u32_e64 v25, vcc, 0, v25, s[8:9]
	v_cmp_ge_f32_e64 s[8:9], v41, v23
	v_addc_co_u32_e64 v24, vcc, 0, v24, s[0:1]
	v_cmp_ge_f32_e64 s[0:1], v40, v23
	v_addc_co_u32_e64 v25, vcc, 0, v25, s[6:7]
	v_addc_co_u32_e64 v24, vcc, 0, v24, s[8:9]
	v_addc_co_u32_e64 v25, vcc, 0, v25, s[0:1]
	v_add_u32_e32 v24, v24, v25
	v_cmp_gt_f32_e64 s[0:1], v23, v21
	v_mov_b32_e32 v25, v24
	v_cmp_lt_f32_e64 s[6:7], v23, v22
	s_nop 1
	v_permlane16_swap_b32_e32 v24, v25
	s_and_b64 s[0:1], s[0:1], s[6:7]
	v_add_u32_e32 v24, v24, v25
	s_andn2_b64 s[6:7], s[0:1], s[4:5]
	v_mov_b32_e32 v25, v24
	s_orn2_b64 s[4:5], s[4:5], s[0:1]
	s_nop 1
	v_permlane32_swap_b32_e32 v24, v25
	s_add_i32 s2, s2, 1
	v_add_u32_e32 v24, v24, v25
	v_cmp_lt_i32_e64 s[8:9], 15, v24
	v_cmp_eq_u32_e64 s[10:11], 16, v24
	s_and_b64 s[0:1], s[6:7], s[8:9]
	s_andn2_b64 s[6:7], s[6:7], s[8:9]
	s_and_b64 s[10:11], s[0:1], s[10:11]
	v_cndmask_b32_e64 v21, v21, v23, s[0:1]
	v_cndmask_b32_e64 v22, v22, v23, s[6:7]
	s_or_b64 s[4:5], s[4:5], s[10:11]
	s_cmp_eq_u64 s[4:5], exec
	s_cbranch_scc1 .LBB0_187
	s_cmp_lt_u32 s2, 64
	s_cbranch_scc1 .LselB_loop

; __device__ __forceinline__ void peer_up_phase(const Ctx& C, const unsigned char* EU, bf16* XBN, float* RSS, float* xio, const float* gfinal, bool last, const float* SELG, const int* SELI) {
;     int gl = threadIdx.x & 63; asm volatile("" : "+v"(gl));
;     for (int wtile = C.gw; wtile < MTOK / 16; wtile += C.ngw) {
;         const int tok0 = wtile * 16;
;         int nvi0 = SELI[(size_t)tok0 * 128 + gl], nvi1 = SELI[(size_t)tok0 * 128 + 64 + gl]; float nvg0 = SELG[(size_t)tok0 * 128 + gl], nvg1 = SELG[(size_t)tok0 * 128 + 64 + gl];
;         for (int ti = 0; ti < 16; ++ti) {
;             const size_t tok = (size_t)tok0 + ti;
;             const int vi0 = nvi0, vi1 = nvi1; const float vg0 = nvg0, vg1 = nvg1;
;             if (ti + 1 < 16) { const size_t tn = tok + 1; nvi0 = SELI[tn * 128 + gl]; nvi1 = SELI[tn * 128 + 64 + gl]; nvg0 = SELG[tn * 128 + gl]; nvg1 = SELG[tn * 128 + 64 + gl]; }
.LBB0_337:
	v_readlane_b32 s0, v247, 53
	v_mov_b32_e32 v142, v177
	s_cmpk_gt_i32 s0, 0xfff
	v_readlane_b32 s1, v247, 54
	s_cbranch_scc1 .LBB0_357
	v_readlane_b32 s0, v247, 56
	s_cmp_lt_u32 s0, 3
	s_cbranch_scc1 .Lup_new
	v_readlane_b32 s0, v247, 56
	v_readlane_b32 s1, v247, 57
	s_cmp_lg_u32 s0, 3
	v_lshlrev_b32_e32 v0, 4, v142
	v_readlane_b32 s0, v249, 37
	v_ashrrev_i32_e32 v1, 31, v0
	v_readlane_b32 s1, v249, 38
	v_readlane_b32 s8, v249, 0
	v_ashrrev_i32_e32 v143, 31, v142
	v_lshl_add_u64 v[144:145], v[0:1], 1, s[60:61]
	v_lshl_add_u64 v[146:147], s[0:1], 0, v[0:1]
	v_lshlrev_b64 v[0:1], 2, v[0:1]
	v_readlane_b32 s12, v249, 4
	v_readlane_b32 s13, v249, 5
	v_readlane_b32 s14, v249, 6
	v_readlane_b32 s15, v249, 7
	s_mov_b64 s[0:1], 0xc0
	s_cselect_b64 s[4:5], -1, 0
	s_waitcnt lgkmcnt(0)
	v_lshl_add_u64 v[148:149], v[142:143], 2, s[92:93]
	v_lshl_add_u64 v[150:151], s[14:15], 0, v[0:1]
	v_lshl_add_u64 v[152:153], v[142:143], 0, s[74:75]
	v_lshl_add_u64 v[154:155], v[142:143], 0, s[0:1]
	v_cmp_gt_i32_e64 s[38:39], 16, v142
	v_cmp_eq_u32_e64 s[40:41], 0, v142
	v_lshl_add_u64 v[156:157], s[12:13], 0, v[0:1]
	v_readlane_b32 s0, v247, 53
	v_readlane_b32 s9, v249, 1
	v_readlane_b32 s10, v249, 2
	v_readlane_b32 s11, v249, 3
	v_readlane_b32 s1, v247, 54
	s_branch .LBB0_340

; __device__ __forceinline__ void peer_up_phase(const Ctx& C, const unsigned char* EU, bf16* XBN, float* RSS, float* xio, const float* gfinal, bool last, const float* SELG, const int* SELI) {
;     int gl = threadIdx.x & 63; asm volatile("" : "+v"(gl));
;     for (int wtile = C.gw; wtile < MTOK / 16; wtile += C.ngw) {
;         const int tok0 = wtile * 16;
;         int nvi0 = SELI[(size_t)tok0 * 128 + gl], nvi1 = SELI[(size_t)tok0 * 128 + 64 + gl]; float nvg0 = SELG[(size_t)tok0 * 128 + gl], nvg1 = SELG[(size_t)tok0 * 128 + 64 + gl];
;         for (int ti = 0; ti < 16; ++ti) {
;             const size_t tok = (size_t)tok0 + ti;
;             const int vi0 = nvi0, vi1 = nvi1; const float vg0 = nvg0, vg1 = nvg1;
;             if (ti + 1 < 16) { const size_t tn = tok + 1; nvi0 = SELI[tn * 128 + gl]; nvi1 = SELI[tn * 128 + 64 + gl]; nvg0 = SELG[tn * 128 + gl]; nvg1 = SELG[tn * 128 + 64 + gl]; }
;             bf16* xr16 = XBN + tok * DM + 16 * gl;
;             const v4u xw0 = __builtin_nontemporal_load((const v4u*)xr16), xw1 = __builtin_nontemporal_load((const v4u*)(xr16 + 8));
;             v2f y[8];
; #pragma unroll
;             for (int k = 0; k < 8; ++k) y[k] = (v2f){0.f, 0.f};
;             v4u upA[8], upB[8];
; #pragma unroll
;             for (int k = 0; k < 8; ++k) { const int e = __builtin_amdgcn_readlane(vi0, k); upA[k] = *(const v4u*)(EU + (size_t)e * DM + 16 * gl); }
; #pragma unroll
;             for (int k = 0; k < 8; ++k) { const int e = __builtin_amdgcn_readlane(vi0, 8 + k); upB[k] = *(const v4u*)(EU + (size_t)e * DM + 16 * gl); }
.Lup_new:
	v_readlane_b32 s0, v247, 53
	v_readlane_b32 s4, v249, 8
	v_readlane_b32 s5, v249, 9
	s_lshr_b32 s1, s0, 3
	s_and_b32 s2, s0, 7
	s_and_b32 s17, s1, 7
	s_lshr_b32 s1, s1, 3
	s_lshr_b32 s15, s98, 6
	s_cmp_ge_u32 s1, s15
	s_cbranch_scc1 .Lup_done
	s_lshl_b32 s14, s1, 3
	s_add_i32 s14, s14, s2
	s_lshl_b32 s15, s15, 3
	s_lshl_b32 s16, s2, 11
	s_add_u32 s6, s4, 0x2b600000
	s_addc_u32 s7, s5, 0
	s_add_u32 s8, s4, 0x6600000
	s_addc_u32 s9, s5, 0
	s_lshl_b32 s0, s17, 21
	s_add_u32 s8, s8, s0
	s_addc_u32 s9, s9, 0
	s_add_u32 s4, s4, 0x2d600000
	s_addc_u32 s5, s5, 0
	s_lshl_b32 s0, s17, 8
	s_add_u32 s10, s60, s0
	s_addc_u32 s11, s61, 0
	s_lshl_b32 s0, s17, 2
	s_add_u32 s12, s92, s0
	s_addc_u32 s13, s93, 0
	v_and_b32_e32 v1, 7, v177
	v_lshlrev_b32_e32 v1, 4, v1
	v_lshrrev_b32_e32 v2, 3, v177
	v_lshlrev_b32_e32 v3, 3, v177
	v_add_u32_e32 v3, s16, v3
	v_lshl_add_u32 v2, v2, 3, s16
	v_lshlrev_b32_e32 v4, 2, v177
	v_and_b32_e32 v5, 7, v177
	v_lshlrev_b32_e32 v5, 5, v5
	v_bfe_u32 v44, v177, 5, 1
	v_lshl_or_b32 v5, v44, 4, v5
	v_bfe_u32 v44, v177, 4, 1
	v_lshl_or_b32 v5, v44, 3, v5
	v_mov_b32_e32 v160, 0
	s_lshl_b32 s2, s14, 9
	s_add_u32 s0, s6, s2
	s_addc_u32 s1, s7, 0
	global_load_dword v6, v4, s[0:1]
	global_load_dword v8, v4, s[0:1] offset:256
	s_add_u32 s0, s4, s2
	s_addc_u32 s1, s5, 0
	global_load_dword v7, v4, s[0:1]
	global_load_dword v9, v4, s[0:1] offset:256
.Lup_tok:
	s_lshl_b32 s2, s14, 11
	s_add_u32 s18, s10, s2
	s_addc_u32 s19, s11, 0
	s_waitcnt vmcnt(0)
	ds_write_b64 v3, v[6:7]
	ds_write_b64 v3, v[8:9] offset:512
	global_load_dwordx2 v[10:11], v5, s[18:19]
	s_add_i32 s20, s14, s15
	s_cmp_lt_u32 s20, 0x10000
	s_cbranch_scc0 .Lup_nopf
	s_lshl_b32 s2, s20, 9
	s_add_u32 s0, s6, s2
	s_addc_u32 s1, s7, 0
	global_load_dword v6, v4, s[0:1]
	global_load_dword v8, v4, s[0:1] offset:256
	s_add_u32 s0, s4, s2
	s_addc_u32 s1, s5, 0
	global_load_dword v7, v4, s[0:1]
	global_load_dword v9, v4, s[0:1] offset:256
.Lup_nopf:
	ds_read_b64 v[12:13], v2
	ds_read_b64 v[14:15], v2 offset:64
	ds_read_b64 v[16:17], v2 offset:128
	ds_read_b64 v[18:19], v2 offset:192
	ds_read_b64 v[20:21], v2 offset:256
	ds_read_b64 v[22:23], v2 offset:320
	ds_read_b64 v[24:25], v2 offset:384
	ds_read_b64 v[26:27], v2 offset:448
	ds_read_b64 v[28:29], v2 offset:512
	ds_read_b64 v[30:31], v2 offset:576
	ds_read_b64 v[32:33], v2 offset:640
	ds_read_b64 v[34:35], v2 offset:704
	ds_read_b64 v[36:37], v2 offset:768
	ds_read_b64 v[38:39], v2 offset:832
	ds_read_b64 v[40:41], v2 offset:896
	ds_read_b64 v[42:43], v2 offset:960
	v_mov_b64_e32 v[112:113], 0
	v_mov_b64_e32 v[114:115], 0
	v_mov_b64_e32 v[116:117], 0
	v_mov_b64_e32 v[118:119], 0
	v_mov_b64_e32 v[120:121], 0
	v_mov_b64_e32 v[122:123], 0
	v_mov_b64_e32 v[124:125], 0
	v_mov_b64_e32 v[126:127], 0
	s_waitcnt lgkmcnt(8)
	v_lshl_add_u32 v13, v13, 7, v1
	global_load_dwordx4 v[48:51], v13, s[8:9]
	v_lshl_add_u32 v15, v15, 7, v1
	global_load_dwordx4 v[52:55], v15, s[8:9]
	v_lshl_add_u32 v17, v17, 7, v1
	global_load_dwordx4 v[56:59], v17, s[8:9]
	v_lshl_add_u32 v19, v19, 7, v1
	global_load_dwordx4 v[60:63], v19, s[8:9]
	v_lshl_add_u32 v21, v21, 7, v1
	global_load_dwordx4 v[64:67], v21, s[8:9]
	v_lshl_add_u32 v23, v23, 7, v1
	global_load_dwordx4 v[68:71], v23, s[8:9]
	v_lshl_add_u32 v25, v25, 7, v1
	global_load_dwordx4 v[72:75], v25, s[8:9]
	v_lshl_add_u32 v27, v27, 7, v1
	global_load_dwordx4 v[76:79], v27, s[8:9]
	s_waitcnt lgkmcnt(0)
	v_lshl_add_u32 v29, v29, 7, v1
	global_load_dwordx4 v[80:83], v29, s[8:9]
	v_lshl_add_u32 v31, v31, 7, v1
	global_load_dwordx4 v[84:87], v31, s[8:9]
	v_lshl_add_u32 v33, v33, 7, v1
	global_load_dwordx4 v[88:91], v33, s[8:9]
	v_lshl_add_u32 v35, v35, 7, v1
	global_load_dwordx4 v[92:95], v35, s[8:9]
	v_lshl_add_u32 v37, v37, 7, v1
	global_load_dwordx4 v[96:99], v37, s[8:9]
	v_lshl_add_u32 v39, v39, 7, v1
	global_load_dwordx4 v[100:103], v39, s[8:9]
	v_lshl_add_u32 v41, v41, 7, v1
	global_load_dwordx4 v[104:107], v41, s[8:9]
	v_lshl_add_u32 v43, v43, 7, v1
	global_load_dwordx4 v[108:111], v43, s[8:9]
	s_waitcnt vmcnt(15)
	v_cvt_pk_f32_fp8_e32 v[144:145], v48
	v_cvt_pk_f32_fp8_sdwa v[146:147], v48 src0_sel:WORD_1
	v_cvt_pk_f32_fp8_e32 v[148:149], v49
	v_cvt_pk_f32_fp8_sdwa v[150:151], v49 src0_sel:WORD_1
	v_cvt_pk_f32_fp8_e32 v[152:153], v50
	v_cvt_pk_f32_fp8_sdwa v[154:155], v50 src0_sel:WORD_1
	v_cvt_pk_f32_fp8_e32 v[156:157], v51
	v_cvt_pk_f32_fp8_sdwa v[158:159], v51 src0_sel:WORD_1
	v_pk_fma_f32 v[112:113], v[144:145], v[12:13], v[112:113] op_sel_hi:[1,0,1]
	v_pk_fma_f32 v[114:115], v[146:147], v[12:13], v[114:115] op_sel_hi:[1,0,1]
	v_pk_fma_f32 v[116:117], v[148:149], v[12:13], v[116:117] op_sel_hi:[1,0,1]
	v_pk_fma_f32 v[118:119], v[150:151], v[12:13], v[118:119] op_sel_hi:[1,0,1]
	v_pk_fma_f32 v[120:121], v[152:153], v[12:13], v[120:121] op_sel_hi:[1,0,1]
	v_pk_fma_f32 v[122:123], v[154:155], v[12:13], v[122:123] op_sel_hi:[1,0,1]
	v_pk_fma_f32 v[124:125], v[156:157], v[12:13], v[124:125] op_sel_hi:[1,0,1]
	v_pk_fma_f32 v[126:127], v[158:159], v[12:13], v[126:127] op_sel_hi:[1,0,1]
	s_waitcnt vmcnt(14)
	v_cvt_pk_f32_fp8_e32 v[144:145], v52
	v_cvt_pk_f32_fp8_sdwa v[146:147], v52 src0_sel:WORD_1
	v_cvt_pk_f32_fp8_e32 v[148:149], v53
	v_cvt_pk_f32_fp8_sdwa v[150:151], v53 src0_sel:WORD_1
	v_cvt_pk_f32_fp8_e32 v[152:153], v54
	v_cvt_pk_f32_fp8_sdwa v[154:155], v54 src0_sel:WORD_1
	v_cvt_pk_f32_fp8_e32 v[156:157], v55
	v_cvt_pk_f32_fp8_sdwa v[158:159], v55 src0_sel:WORD_1
	v_pk_fma_f32 v[112:113], v[144:145], v[14:15], v[112:113] op_sel_hi:[1,0,1]
	v_pk_fma_f32 v[114:115], v[146:147], v[14:15], v[114:115] op_sel_hi:[1,0,1]
	v_pk_fma_f32 v[116:117], v[148:149], v[14:15], v[116:117] op_sel_hi:[1,0,1]
	v_pk_fma_f32 v[118:119], v[150:151], v[14:15], v[118:119] op_sel_hi:[1,0,1]
	v_pk_fma_f32 v[120:121], v[152:153], v[14:15], v[120:121] op_sel_hi:[1,0,1]
	v_pk_fma_f32 v[122:123], v[154:155], v[14:15], v[122:123] op_sel_hi:[1,0,1]
	v_pk_fma_f32 v[124:125], v[156:157], v[14:15], v[124:125] op_sel_hi:[1,0,1]
	v_pk_fma_f32 v[126:127], v[158:159], v[14:15], v[126:127] op_sel_hi:[1,0,1]
	s_waitcnt vmcnt(13)
	v_cvt_pk_f32_fp8_e32 v[144:145], v56
	v_cvt_pk_f32_fp8_sdwa v[146:147], v56 src0_sel:WORD_1
	v_cvt_pk_f32_fp8_e32 v[148:149], v57
	v_cvt_pk_f32_fp8_sdwa v[150:151], v57 src0_sel:WORD_1
	v_cvt_pk_f32_fp8_e32 v[152:153], v58
	v_cvt_pk_f32_fp8_sdwa v[154:155], v58 src0_sel:WORD_1
	v_cvt_pk_f32_fp8_e32 v[156:157], v59
	v_cvt_pk_f32_fp8_sdwa v[158:159], v59 src0_sel:WORD_1
	v_pk_fma_f32 v[112:113], v[144:145], v[16:17], v[112:113] op_sel_hi:[1,0,1]
	v_pk_fma_f32 v[114:115], v[146:147], v[16:17], v[114:115] op_sel_hi:[1,0,1]
	v_pk_fma_f32 v[116:117], v[148:149], v[16:17], v[116:117] op_sel_hi:[1,0,1]
	v_pk_fma_f32 v[118:119], v[150:151], v[16:17], v[118:119] op_sel_hi:[1,0,1]
	v_pk_fma_f32 v[120:121], v[152:153], v[16:17], v[120:121] op_sel_hi:[1,0,1]
	v_pk_fma_f32 v[122:123], v[154:155], v[16:17], v[122:123] op_sel_hi:[1,0,1]
	v_pk_fma_f32 v[124:125], v[156:157], v[16:17], v[124:125] op_sel_hi:[1,0,1]
	v_pk_fma_f32 v[126:127], v[158:159], v[16:17], v[126:127] op_sel_hi:[1,0,1]
	s_waitcnt vmcnt(12)
	v_cvt_pk_f32_fp8_e32 v[144:145], v60
	v_cvt_pk_f32_fp8_sdwa v[146:147], v60 src0_sel:WORD_1
	v_cvt_pk_f32_fp8_e32 v[148:149], v61
	v_cvt_pk_f32_fp8_sdwa v[150:151], v61 src0_sel:WORD_1
	v_cvt_pk_f32_fp8_e32 v[152:153], v62
	v_cvt_pk_f32_fp8_sdwa v[154:155], v62 src0_sel:WORD_1
	v_cvt_pk_f32_fp8_e32 v[156:157], v63
	v_cvt_pk_f32_fp8_sdwa v[158:159], v63 src0_sel:WORD_1
	v_pk_fma_f32 v[112:113], v[144:145], v[18:19], v[112:113] op_sel_hi:[1,0,1]
	v_pk_fma_f32 v[114:115], v[146:147], v[18:19], v[114:115] op_sel_hi:[1,0,1]
	v_pk_fma_f32 v[116:117], v[148:149], v[18:19], v[116:117] op_sel_hi:[1,0,1]
	v_pk_fma_f32 v[118:119], v[150:151], v[18:19], v[118:119] op_sel_hi:[1,0,1]
	v_pk_fma_f32 v[120:121], v[152:153], v[18:19], v[120:121] op_sel_hi:[1,0,1]
	v_pk_fma_f32 v[122:123], v[154:155], v[18:19], v[122:123] op_sel_hi:[1,0,1]
	v_pk_fma_f32 v[124:125], v[156:157], v[18:19], v[124:125] op_sel_hi:[1,0,1]
	v_pk_fma_f32 v[126:127], v[158:159], v[18:19], v[126:127] op_sel_hi:[1,0,1]
	s_waitcnt vmcnt(11)
	v_cvt_pk_f32_fp8_e32 v[144:145], v64
	v_cvt_pk_f32_fp8_sdwa v[146:147], v64 src0_sel:WORD_1
	v_cvt_pk_f32_fp8_e32 v[148:149], v65
	v_cvt_pk_f32_fp8_sdwa v[150:151], v65 src0_sel:WORD_1
	v_cvt_pk_f32_fp8_e32 v[152:153], v66
	v_cvt_pk_f32_fp8_sdwa v[154:155], v66 src0_sel:WORD_1
	v_cvt_pk_f32_fp8_e32 v[156:157], v67
	v_cvt_pk_f32_fp8_sdwa v[158:159], v67 src0_sel:WORD_1
	v_pk_fma_f32 v[112:113], v[144:145], v[20:21], v[112:113] op_sel_hi:[1,0,1]
	v_pk_fma_f32 v[114:115], v[146:147], v[20:21], v[114:115] op_sel_hi:[1,0,1]
	v_pk_fma_f32 v[116:117], v[148:149], v[20:21], v[116:117] op_sel_hi:[1,0,1]
	v_pk_fma_f32 v[118:119], v[150:151], v[20:21], v[118:119] op_sel_hi:[1,0,1]
	v_pk_fma_f32 v[120:121], v[152:153], v[20:21], v[120:121] op_sel_hi:[1,0,1]
	v_pk_fma_f32 v[122:123], v[154:155], v[20:21], v[122:123] op_sel_hi:[1,0,1]
	v_pk_fma_f32 v[124:125], v[156:157], v[20:21], v[124:125] op_sel_hi:[1,0,1]
	v_pk_fma_f32 v[126:127], v[158:159], v[20:21], v[126:127] op_sel_hi:[1,0,1]
	s_waitcnt vmcnt(10)
	v_cvt_pk_f32_fp8_e32 v[144:145], v68
	v_cvt_pk_f32_fp8_sdwa v[146:147], v68 src0_sel:WORD_1
	v_cvt_pk_f32_fp8_e32 v[148:149], v69
	v_cvt_pk_f32_fp8_sdwa v[150:151], v69 src0_sel:WORD_1
	v_cvt_pk_f32_fp8_e32 v[152:153], v70
	v_cvt_pk_f32_fp8_sdwa v[154:155], v70 src0_sel:WORD_1
	v_cvt_pk_f32_fp8_e32 v[156:157], v71
	v_cvt_pk_f32_fp8_sdwa v[158:159], v71 src0_sel:WORD_1
	v_pk_fma_f32 v[112:113], v[144:145], v[22:23], v[112:113] op_sel_hi:[1,0,1]
	v_pk_fma_f32 v[114:115], v[146:147], v[22:23], v[114:115] op_sel_hi:[1,0,1]
	v_pk_fma_f32 v[116:117], v[148:149], v[22:23], v[116:117] op_sel_hi:[1,0,1]
	v_pk_fma_f32 v[118:119], v[150:151], v[22:23], v[118:119] op_sel_hi:[1,0,1]
	v_pk_fma_f32 v[120:121], v[152:153], v[22:23], v[120:121] op_sel_hi:[1,0,1]
	v_pk_fma_f32 v[122:123], v[154:155], v[22:23], v[122:123] op_sel_hi:[1,0,1]
	v_pk_fma_f32 v[124:125], v[156:157], v[22:23], v[124:125] op_sel_hi:[1,0,1]
	v_pk_fma_f32 v[126:127], v[158:159], v[22:23], v[126:127] op_sel_hi:[1,0,1]
	s_waitcnt vmcnt(9)
	v_cvt_pk_f32_fp8_e32 v[144:145], v72
	v_cvt_pk_f32_fp8_sdwa v[146:147], v72 src0_sel:WORD_1
	v_cvt_pk_f32_fp8_e32 v[148:149], v73
	v_cvt_pk_f32_fp8_sdwa v[150:151], v73 src0_sel:WORD_1
	v_cvt_pk_f32_fp8_e32 v[152:153], v74
	v_cvt_pk_f32_fp8_sdwa v[154:155], v74 src0_sel:WORD_1
	v_cvt_pk_f32_fp8_e32 v[156:157], v75
	v_cvt_pk_f32_fp8_sdwa v[158:159], v75 src0_sel:WORD_1
	v_pk_fma_f32 v[112:113], v[144:145], v[24:25], v[112:113] op_sel_hi:[1,0,1]
	v_pk_fma_f32 v[114:115], v[146:147], v[24:25], v[114:115] op_sel_hi:[1,0,1]
	v_pk_fma_f32 v[116:117], v[148:149], v[24:25], v[116:117] op_sel_hi:[1,0,1]
	v_pk_fma_f32 v[118:119], v[150:151], v[24:25], v[118:119] op_sel_hi:[1,0,1]
	v_pk_fma_f32 v[120:121], v[152:153], v[24:25], v[120:121] op_sel_hi:[1,0,1]
	v_pk_fma_f32 v[122:123], v[154:155], v[24:25], v[122:123] op_sel_hi:[1,0,1]
	v_pk_fma_f32 v[124:125], v[156:157], v[24:25], v[124:125] op_sel_hi:[1,0,1]
	v_pk_fma_f32 v[126:127], v[158:159], v[24:25], v[126:127] op_sel_hi:[1,0,1]
	s_waitcnt vmcnt(8)
	v_cvt_pk_f32_fp8_e32 v[144:145], v76
	v_cvt_pk_f32_fp8_sdwa v[146:147], v76 src0_sel:WORD_1
	v_cvt_pk_f32_fp8_e32 v[148:149], v77
	v_cvt_pk_f32_fp8_sdwa v[150:151], v77 src0_sel:WORD_1
	v_cvt_pk_f32_fp8_e32 v[152:153], v78
	v_cvt_pk_f32_fp8_sdwa v[154:155], v78 src0_sel:WORD_1
	v_cvt_pk_f32_fp8_e32 v[156:157], v79
	v_cvt_pk_f32_fp8_sdwa v[158:159], v79 src0_sel:WORD_1
	v_pk_fma_f32 v[112:113], v[144:145], v[26:27], v[112:113] op_sel_hi:[1,0,1]
	v_pk_fma_f32 v[114:115], v[146:147], v[26:27], v[114:115] op_sel_hi:[1,0,1]
	v_pk_fma_f32 v[116:117], v[148:149], v[26:27], v[116:117] op_sel_hi:[1,0,1]
	v_pk_fma_f32 v[118:119], v[150:151], v[26:27], v[118:119] op_sel_hi:[1,0,1]
	v_pk_fma_f32 v[120:121], v[152:153], v[26:27], v[120:121] op_sel_hi:[1,0,1]
	v_pk_fma_f32 v[122:123], v[154:155], v[26:27], v[122:123] op_sel_hi:[1,0,1]
	v_pk_fma_f32 v[124:125], v[156:157], v[26:27], v[124:125] op_sel_hi:[1,0,1]
	v_pk_fma_f32 v[126:127], v[158:159], v[26:27], v[126:127] op_sel_hi:[1,0,1]
	s_waitcnt vmcnt(7)
	v_cvt_pk_f32_fp8_e32 v[144:145], v80
	v_cvt_pk_f32_fp8_sdwa v[146:147], v80 src0_sel:WORD_1
	v_cvt_pk_f32_fp8_e32 v[148:149], v81
	v_cvt_pk_f32_fp8_sdwa v[150:151], v81 src0_sel:WORD_1
	v_cvt_pk_f32_fp8_e32 v[152:153], v82
	v_cvt_pk_f32_fp8_sdwa v[154:155], v82 src0_sel:WORD_1
	v_cvt_pk_f32_fp8_e32 v[156:157], v83
	v_cvt_pk_f32_fp8_sdwa v[158:159], v83 src0_sel:WORD_1
	v_pk_fma_f32 v[112:113], v[144:145], v[28:29], v[112:113] op_sel_hi:[1,0,1]
	v_pk_fma_f32 v[114:115], v[146:147], v[28:29], v[114:115] op_sel_hi:[1,0,1]
	v_pk_fma_f32 v[116:117], v[148:149], v[28:29], v[116:117] op_sel_hi:[1,0,1]
	v_pk_fma_f32 v[118:119], v[150:151], v[28:29], v[118:119] op_sel_hi:[1,0,1]
	v_pk_fma_f32 v[120:121], v[152:153], v[28:29], v[120:121] op_sel_hi:[1,0,1]
	v_pk_fma_f32 v[122:123], v[154:155], v[28:29], v[122:123] op_sel_hi:[1,0,1]
	v_pk_fma_f32 v[124:125], v[156:157], v[28:29], v[124:125] op_sel_hi:[1,0,1]
	v_pk_fma_f32 v[126:127], v[158:159], v[28:29], v[126:127] op_sel_hi:[1,0,1]
	s_waitcnt vmcnt(6)
	v_cvt_pk_f32_fp8_e32 v[144:145], v84
	v_cvt_pk_f32_fp8_sdwa v[146:147], v84 src0_sel:WORD_1
	v_cvt_pk_f32_fp8_e32 v[148:149], v85
	v_cvt_pk_f32_fp8_sdwa v[150:151], v85 src0_sel:WORD_1
	v_cvt_pk_f32_fp8_e32 v[152:153], v86
	v_cvt_pk_f32_fp8_sdwa v[154:155], v86 src0_sel:WORD_1
	v_cvt_pk_f32_fp8_e32 v[156:157], v87
	v_cvt_pk_f32_fp8_sdwa v[158:159], v87 src0_sel:WORD_1
	v_pk_fma_f32 v[112:113], v[144:145], v[30:31], v[112:113] op_sel_hi:[1,0,1]
	v_pk_fma_f32 v[114:115], v[146:147], v[30:31], v[114:115] op_sel_hi:[1,0,1]
	v_pk_fma_f32 v[116:117], v[148:149], v[30:31], v[116:117] op_sel_hi:[1,0,1]
	v_pk_fma_f32 v[118:119], v[150:151], v[30:31], v[118:119] op_sel_hi:[1,0,1]
	v_pk_fma_f32 v[120:121], v[152:153], v[30:31], v[120:121] op_sel_hi:[1,0,1]
	v_pk_fma_f32 v[122:123], v[154:155], v[30:31], v[122:123] op_sel_hi:[1,0,1]
	v_pk_fma_f32 v[124:125], v[156:157], v[30:31], v[124:125] op_sel_hi:[1,0,1]
	v_pk_fma_f32 v[126:127], v[158:159], v[30:31], v[126:127] op_sel_hi:[1,0,1]
	s_waitcnt vmcnt(5)
	v_cvt_pk_f32_fp8_e32 v[144:145], v88
	v_cvt_pk_f32_fp8_sdwa v[146:147], v88 src0_sel:WORD_1
	v_cvt_pk_f32_fp8_e32 v[148:149], v89
	v_cvt_pk_f32_fp8_sdwa v[150:151], v89 src0_sel:WORD_1
	v_cvt_pk_f32_fp8_e32 v[152:153], v90
	v_cvt_pk_f32_fp8_sdwa v[154:155], v90 src0_sel:WORD_1
	v_cvt_pk_f32_fp8_e32 v[156:157], v91
	v_cvt_pk_f32_fp8_sdwa v[158:159], v91 src0_sel:WORD_1
	v_pk_fma_f32 v[112:113], v[144:145], v[32:33], v[112:113] op_sel_hi:[1,0,1]
	v_pk_fma_f32 v[114:115], v[146:147], v[32:33], v[114:115] op_sel_hi:[1,0,1]
	v_pk_fma_f32 v[116:117], v[148:149], v[32:33], v[116:117] op_sel_hi:[1,0,1]
	v_pk_fma_f32 v[118:119], v[150:151], v[32:33], v[118:119] op_sel_hi:[1,0,1]
	v_pk_fma_f32 v[120:121], v[152:153], v[32:33], v[120:121] op_sel_hi:[1,0,1]
	v_pk_fma_f32 v[122:123], v[154:155], v[32:33], v[122:123] op_sel_hi:[1,0,1]
	v_pk_fma_f32 v[124:125], v[156:157], v[32:33], v[124:125] op_sel_hi:[1,0,1]
	v_pk_fma_f32 v[126:127], v[158:159], v[32:33], v[126:127] op_sel_hi:[1,0,1]
	s_waitcnt vmcnt(4)
	v_cvt_pk_f32_fp8_e32 v[144:145], v92
	v_cvt_pk_f32_fp8_sdwa v[146:147], v92 src0_sel:WORD_1
	v_cvt_pk_f32_fp8_e32 v[148:149], v93
	v_cvt_pk_f32_fp8_sdwa v[150:151], v93 src0_sel:WORD_1
	v_cvt_pk_f32_fp8_e32 v[152:153], v94
	v_cvt_pk_f32_fp8_sdwa v[154:155], v94 src0_sel:WORD_1
	v_cvt_pk_f32_fp8_e32 v[156:157], v95
	v_cvt_pk_f32_fp8_sdwa v[158:159], v95 src0_sel:WORD_1
	v_pk_fma_f32 v[112:113], v[144:145], v[34:35], v[112:113] op_sel_hi:[1,0,1]
	v_pk_fma_f32 v[114:115], v[146:147], v[34:35], v[114:115] op_sel_hi:[1,0,1]
	v_pk_fma_f32 v[116:117], v[148:149], v[34:35], v[116:117] op_sel_hi:[1,0,1]
	v_pk_fma_f32 v[118:119], v[150:151], v[34:35], v[118:119] op_sel_hi:[1,0,1]
	v_pk_fma_f32 v[120:121], v[152:153], v[34:35], v[120:121] op_sel_hi:[1,0,1]
	v_pk_fma_f32 v[122:123], v[154:155], v[34:35], v[122:123] op_sel_hi:[1,0,1]
	v_pk_fma_f32 v[124:125], v[156:157], v[34:35], v[124:125] op_sel_hi:[1,0,1]
	v_pk_fma_f32 v[126:127], v[158:159], v[34:35], v[126:127] op_sel_hi:[1,0,1]
	s_waitcnt vmcnt(3)
	v_cvt_pk_f32_fp8_e32 v[144:145], v96
	v_cvt_pk_f32_fp8_sdwa v[146:147], v96 src0_sel:WORD_1
	v_cvt_pk_f32_fp8_e32 v[148:149], v97
	v_cvt_pk_f32_fp8_sdwa v[150:151], v97 src0_sel:WORD_1
	v_cvt_pk_f32_fp8_e32 v[152:153], v98
	v_cvt_pk_f32_fp8_sdwa v[154:155], v98 src0_sel:WORD_1
	v_cvt_pk_f32_fp8_e32 v[156:157], v99
	v_cvt_pk_f32_fp8_sdwa v[158:159], v99 src0_sel:WORD_1
	v_pk_fma_f32 v[112:113], v[144:145], v[36:37], v[112:113] op_sel_hi:[1,0,1]
	v_pk_fma_f32 v[114:115], v[146:147], v[36:37], v[114:115] op_sel_hi:[1,0,1]
	v_pk_fma_f32 v[116:117], v[148:149], v[36:37], v[116:117] op_sel_hi:[1,0,1]
	v_pk_fma_f32 v[118:119], v[150:151], v[36:37], v[118:119] op_sel_hi:[1,0,1]
	v_pk_fma_f32 v[120:121], v[152:153], v[36:37], v[120:121] op_sel_hi:[1,0,1]
	v_pk_fma_f32 v[122:123], v[154:155], v[36:37], v[122:123] op_sel_hi:[1,0,1]
	v_pk_fma_f32 v[124:125], v[156:157], v[36:37], v[124:125] op_sel_hi:[1,0,1]
	v_pk_fma_f32 v[126:127], v[158:159], v[36:37], v[126:127] op_sel_hi:[1,0,1]
	s_waitcnt vmcnt(2)
; __device__ __forceinline__ void peer_up_phase(const Ctx& C, const unsigned char* EU, bf16* XBN, float* RSS, float* xio, const float* gfinal, bool last, const float* SELG, const int* SELI) {
;     ...
;             for (int grp = 0; grp < 16; grp += 2) { USTEP(upA, grp); USTEP(upB, grp + 1); }
;     ...
;             f32x4 x0 = (f32x4){bflo(xw0[0]), bfhi(xw0[0]), bflo(xw0[1]), bfhi(xw0[1])}, x1 = (f32x4){bflo(xw0[2]), bfhi(xw0[2]), bflo(xw0[3]), bfhi(xw0[3])};
;             f32x4 x2 = (f32x4){bflo(xw1[0]), bfhi(xw1[0]), bflo(xw1[1]), bfhi(xw1[1])}, x3 = (f32x4){bflo(xw1[2]), bfhi(xw1[2]), bflo(xw1[3]), bfhi(xw1[3])};
;             x0 += (f32x4){y[0].x, y[0].y, y[1].x, y[1].y}; x1 += (f32x4){y[2].x, y[2].y, y[3].x, y[3].y}; x2 += (f32x4){y[4].x, y[4].y, y[5].x, y[5].y}; x3 += (f32x4){y[6].x, y[6].y, y[7].x, y[7].y};
;             if (last) {
;                 const float ss = (x0.x * x0.x + x0.y * x0.y) + (x0.z * x0.z + x0.w * x0.w) + (x1.x * x1.x + x1.y * x1.y) + (x1.z * x1.z + x1.w * x1.w)
;                                + (x2.x * x2.x + x2.y * x2.y) + (x2.z * x2.z + x2.w * x2.w) + (x3.x * x3.x + x3.y * x3.y) + (x3.z * x3.z + x3.w * x3.w);
;                 const float rstd = 1.0f / sqrtf(wave_sum(ss) * (1.f / DM) + RMS_EPS);
;                 float* xr = xio + tok * DM + 16 * gl;
;                 const float* gp = gfinal + 16 * gl;
;                 const f32x4 g0 = *(const f32x4*)gp, g1 = *(const f32x4*)(gp + 4), g2 = *(const f32x4*)(gp + 8), g3 = *(const f32x4*)(gp + 12);
;                 __builtin_nontemporal_store(x0 * rstd * g0, (f32x4*)xr); __builtin_nontemporal_store(x1 * rstd * g1, (f32x4*)(xr + 4)); __builtin_nontemporal_store(x2 * rstd * g2, (f32x4*)(xr + 8)); __builtin_nontemporal_store(x3 * rstd * g3, (f32x4*)(xr + 12));
;             } else {
;                 v4u w0, w1; w0.x = pk2(x0.x, x0.y); w0.y = pk2(x0.z, x0.w); w0.z = pk2(x1.x, x1.y); w0.w = pk2(x1.z, x1.w);
;                 w1.x = pk2(x2.x, x2.y); w1.y = pk2(x2.z, x2.w); w1.z = pk2(x3.x, x3.y); w1.w = pk2(x3.z, x3.w);
;                 float ss = 0.f;
; #pragma unroll
;                 for (int w = 0; w < 4; ++w) { const float a0 = bflo(w0[w]), a1 = bfhi(w0[w]), b0 = bflo(w1[w]), b1 = bfhi(w1[w]); ss += (a0 * a0 + a1 * a1) + (b0 * b0 + b1 * b1); }
;                 const float sst = wave_sum(ss);
;                 *(v4u*)xr16 = w0; *(v4u*)(xr16 + 8) = w1;
	v_cvt_pk_f32_fp8_e32 v[144:145], v100
	v_cvt_pk_f32_fp8_sdwa v[146:147], v100 src0_sel:WORD_1
	v_cvt_pk_f32_fp8_e32 v[148:149], v101
	v_cvt_pk_f32_fp8_sdwa v[150:151], v101 src0_sel:WORD_1
	v_cvt_pk_f32_fp8_e32 v[152:153], v102
	v_cvt_pk_f32_fp8_sdwa v[154:155], v102 src0_sel:WORD_1
	v_cvt_pk_f32_fp8_e32 v[156:157], v103
	v_cvt_pk_f32_fp8_sdwa v[158:159], v103 src0_sel:WORD_1
	v_pk_fma_f32 v[112:113], v[144:145], v[38:39], v[112:113] op_sel_hi:[1,0,1]
	v_pk_fma_f32 v[114:115], v[146:147], v[38:39], v[114:115] op_sel_hi:[1,0,1]
	v_pk_fma_f32 v[116:117], v[148:149], v[38:39], v[116:117] op_sel_hi:[1,0,1]
	v_pk_fma_f32 v[118:119], v[150:151], v[38:39], v[118:119] op_sel_hi:[1,0,1]
	v_pk_fma_f32 v[120:121], v[152:153], v[38:39], v[120:121] op_sel_hi:[1,0,1]
	v_pk_fma_f32 v[122:123], v[154:155], v[38:39], v[122:123] op_sel_hi:[1,0,1]
	v_pk_fma_f32 v[124:125], v[156:157], v[38:39], v[124:125] op_sel_hi:[1,0,1]
	v_pk_fma_f32 v[126:127], v[158:159], v[38:39], v[126:127] op_sel_hi:[1,0,1]
	s_waitcnt vmcnt(1)
	v_cvt_pk_f32_fp8_e32 v[144:145], v104
	v_cvt_pk_f32_fp8_sdwa v[146:147], v104 src0_sel:WORD_1
	v_cvt_pk_f32_fp8_e32 v[148:149], v105
	v_cvt_pk_f32_fp8_sdwa v[150:151], v105 src0_sel:WORD_1
	v_cvt_pk_f32_fp8_e32 v[152:153], v106
	v_cvt_pk_f32_fp8_sdwa v[154:155], v106 src0_sel:WORD_1
	v_cvt_pk_f32_fp8_e32 v[156:157], v107
	v_cvt_pk_f32_fp8_sdwa v[158:159], v107 src0_sel:WORD_1
	v_pk_fma_f32 v[112:113], v[144:145], v[40:41], v[112:113] op_sel_hi:[1,0,1]
	v_pk_fma_f32 v[114:115], v[146:147], v[40:41], v[114:115] op_sel_hi:[1,0,1]
	v_pk_fma_f32 v[116:117], v[148:149], v[40:41], v[116:117] op_sel_hi:[1,0,1]
	v_pk_fma_f32 v[118:119], v[150:151], v[40:41], v[118:119] op_sel_hi:[1,0,1]
	v_pk_fma_f32 v[120:121], v[152:153], v[40:41], v[120:121] op_sel_hi:[1,0,1]
	v_pk_fma_f32 v[122:123], v[154:155], v[40:41], v[122:123] op_sel_hi:[1,0,1]
	v_pk_fma_f32 v[124:125], v[156:157], v[40:41], v[124:125] op_sel_hi:[1,0,1]
	v_pk_fma_f32 v[126:127], v[158:159], v[40:41], v[126:127] op_sel_hi:[1,0,1]
	s_waitcnt vmcnt(0)
	v_cvt_pk_f32_fp8_e32 v[144:145], v108
	v_cvt_pk_f32_fp8_sdwa v[146:147], v108 src0_sel:WORD_1
	v_cvt_pk_f32_fp8_e32 v[148:149], v109
	v_cvt_pk_f32_fp8_sdwa v[150:151], v109 src0_sel:WORD_1
	v_cvt_pk_f32_fp8_e32 v[152:153], v110
	v_cvt_pk_f32_fp8_sdwa v[154:155], v110 src0_sel:WORD_1
	v_cvt_pk_f32_fp8_e32 v[156:157], v111
	v_cvt_pk_f32_fp8_sdwa v[158:159], v111 src0_sel:WORD_1
	v_pk_fma_f32 v[112:113], v[144:145], v[42:43], v[112:113] op_sel_hi:[1,0,1]
	v_pk_fma_f32 v[114:115], v[146:147], v[42:43], v[114:115] op_sel_hi:[1,0,1]
	v_pk_fma_f32 v[116:117], v[148:149], v[42:43], v[116:117] op_sel_hi:[1,0,1]
	v_pk_fma_f32 v[118:119], v[150:151], v[42:43], v[118:119] op_sel_hi:[1,0,1]
	v_pk_fma_f32 v[120:121], v[152:153], v[42:43], v[120:121] op_sel_hi:[1,0,1]
	v_pk_fma_f32 v[122:123], v[154:155], v[42:43], v[122:123] op_sel_hi:[1,0,1]
	v_pk_fma_f32 v[124:125], v[156:157], v[42:43], v[124:125] op_sel_hi:[1,0,1]
	v_pk_fma_f32 v[126:127], v[158:159], v[42:43], v[126:127] op_sel_hi:[1,0,1]
	s_nop 1
	v_permlane32_swap_b32_e32 v112, v120
	v_permlane32_swap_b32_e32 v113, v121
	v_permlane32_swap_b32_e32 v114, v122
	v_permlane32_swap_b32_e32 v115, v123
	v_permlane32_swap_b32_e32 v116, v124
	v_permlane32_swap_b32_e32 v117, v125
	v_permlane32_swap_b32_e32 v118, v126
	v_permlane32_swap_b32_e32 v119, v127
	v_add_f32_e32 v112, v112, v120
	v_add_f32_e32 v113, v113, v121
	v_add_f32_e32 v114, v114, v122
	v_add_f32_e32 v115, v115, v123
	v_add_f32_e32 v116, v116, v124
	v_add_f32_e32 v117, v117, v125
	v_add_f32_e32 v118, v118, v126
	v_add_f32_e32 v119, v119, v127
	s_nop 1
	v_permlane16_swap_b32_e32 v112, v116
	v_permlane16_swap_b32_e32 v113, v117
	v_permlane16_swap_b32_e32 v114, v118
	v_permlane16_swap_b32_e32 v115, v119
	v_add_f32_e32 v112, v112, v116
	v_add_f32_e32 v113, v113, v117
	v_add_f32_e32 v114, v114, v118
	v_add_f32_e32 v115, v115, v119
	s_nop 1
	v_add_f32_dpp v112, v112, v112 row_ror:8 row_mask:0xf bank_mask:0xf
	v_add_f32_dpp v113, v113, v113 row_ror:8 row_mask:0xf bank_mask:0xf
	v_add_f32_dpp v114, v114, v114 row_ror:8 row_mask:0xf bank_mask:0xf
	v_add_f32_dpp v115, v115, v115 row_ror:8 row_mask:0xf bank_mask:0xf
	v_lshlrev_b32_e32 v44, 16, v10
	v_and_b32_e32 v45, 0xffff0000, v10
	v_lshlrev_b32_e32 v46, 16, v11
	v_and_b32_e32 v47, 0xffff0000, v11
	v_add_f32_e32 v44, v44, v112
	v_add_f32_e32 v45, v45, v113
	v_add_f32_e32 v46, v46, v114
	v_add_f32_e32 v47, v47, v115
	v_cvt_pk_bf16_f32 v10, v44, v45
	v_cvt_pk_bf16_f32 v11, v46, v47
	s_lshl_b32 s2, s14, 6
	s_add_u32 s0, s12, s2
	s_addc_u32 s1, s13, 0
	global_store_dwordx2 v5, v[10:11], s[18:19]
	v_lshlrev_b32_e32 v44, 16, v10
	v_and_b32_e32 v45, 0xffff0000, v10
	v_lshlrev_b32_e32 v46, 16, v11
	v_and_b32_e32 v47, 0xffff0000, v11
	v_mul_f32_e32 v44, v44, v44
	v_fmac_f32_e32 v44, v45, v45
	v_fmac_f32_e32 v44, v46, v46
	v_fmac_f32_e32 v44, v47, v47
	s_nop 1
	v_add_f32_dpp v44, v44, v44 quad_perm:[1,0,3,2] row_mask:0xf bank_mask:0xf
	s_nop 1
	v_add_f32_dpp v44, v44, v44 quad_perm:[2,3,0,1] row_mask:0xf bank_mask:0xf
	s_nop 1
	v_add_f32_dpp v44, v44, v44 row_half_mirror row_mask:0xf bank_mask:0xf
	v_mov_b32_e32 v45, v44
	s_nop 1
	v_permlane16_swap_b32_e32 v44, v45
	v_add_f32_e32 v44, v44, v45
	v_mov_b32_e32 v45, v44
	s_nop 1
	v_permlane32_swap_b32_e32 v44, v45
	v_add_f32_e32 v44, v44, v45
	s_mov_b64 exec, 1
	global_store_dword v160, v44, s[0:1]
	global_store_dword v160, v160, s[0:1] offset:32
	s_mov_b64 exec, -1
	s_add_i32 s14, s14, s15
	s_cmp_lt_u32 s14, 0x10000
	s_cbranch_scc1 .Lup_tok
.Lup_done:
.LBB0_356:
	v_readlane_b32 s34, v247, 42
	v_readlane_b32 s36, v247, 48
	v_readlane_b32 s38, v247, 50
	v_readlane_b32 s35, v247, 43
	v_readlane_b32 s37, v247, 49
	v_readlane_b32 s39, v247, 51
